# speedup vs baseline: 1.0101x; 1.0101x over previous
; __device__ __forceinline__ int opq(int x) { asm volatile("" : "+v"(x)); return x; }
; __device__ __forceinline__ int crow(int r, int hi) { return (r & 3) + 8 * (r >> 2) + 4 * hi; }
; __device__ __forceinline__ void attn_stream(const u16* __restrict__ Qb, const u16* __restrict__ Kh, const u16* __restrict__ Vh,
;                                             int seq, char* lds, f32x16 (&o)[4]) {
;     ...
;   if (hi == 0) li_l[r32] = l_reg;
;   asm volatile("s_waitcnt lgkmcnt(0)" ::: "memory");
; #pragma unroll
;   for (int r = 0; r < 16; ++r) { const float rl = __builtin_amdgcn_rcpf(li_l[crow(r, hi)]);
; #pragma unroll
;     for (int d0 = 0; d0 < 4; ++d0) o[d0][r] *= rl; }
; __device__ __forceinline__ void phase3(const Params& p, char* shm) {
;     ...
;     { f32x4* o1p = reinterpret_cast<f32x4*>(o1s + opq((int)threadIdx.x) * 64);
; #pragma unroll
;       for (int d0 = 0; d0 < 4; ++d0)
; #pragma unroll
;         for (int q = 0; q < 4; ++q) o1p[d0 * 4 + q] = f32x4{o[d0][q * 4], o[d0][q * 4 + 1], o[d0][q * 4 + 2], o[d0][q * 4 + 3]}; }
.LBB0_361:
	s_or_b64 exec, exec, s[6:7]
	s_and_saveexec_b64 s[0:1], s[4:5]
	ds_write_b32 v212, v192
	s_or_b64 exec, exec, s[0:1]
	s_waitcnt lgkmcnt(0)
	v_add_u32_e32 v76, v204, v190
	ds_read_b128 v[66:69], v76
	ds_read_b128 v[70:73], v76 offset:32
	s_waitcnt lgkmcnt(1)
	v_rcp_f32_e32 v66, v66
	v_rcp_f32_e32 v67, v67
	v_rcp_f32_e32 v68, v68
	v_rcp_f32_e32 v69, v69
	s_waitcnt lgkmcnt(0)
	v_rcp_f32_e32 v70, v70
	v_pk_mul_f32 v[2:3], v[2:3], v[66:67]
	v_pk_mul_f32 v[50:51], v[50:51], v[66:67]
	v_pk_mul_f32 v[34:35], v[34:35], v[66:67]
	v_pk_mul_f32 v[18:19], v[18:19], v[66:67]
	v_pk_mul_f32 v[4:5], v[4:5], v[68:69]
	v_rcp_f32_e32 v71, v71
	v_pk_mul_f32 v[52:53], v[52:53], v[68:69]
	v_pk_mul_f32 v[36:37], v[36:37], v[68:69]
	v_pk_mul_f32 v[20:21], v[20:21], v[68:69]
	ds_read_b128 v[66:69], v76 offset:64
	v_pk_mul_f32 v[6:7], v[6:7], v[70:71]
	v_pk_mul_f32 v[54:55], v[54:55], v[70:71]
	v_rcp_f32_e32 v74, v72
	v_rcp_f32_e32 v75, v73
	v_pk_mul_f32 v[38:39], v[38:39], v[70:71]
	v_pk_mul_f32 v[22:23], v[22:23], v[70:71]
	ds_read_b128 v[70:73], v76 offset:96
	s_waitcnt lgkmcnt(1)
	v_rcp_f32_e32 v66, v66
	v_rcp_f32_e32 v67, v67
	v_rcp_f32_e32 v68, v68
	v_rcp_f32_e32 v69, v69
	v_pk_mul_f32 v[40:41], v[40:41], v[74:75]
	v_pk_mul_f32 v[10:11], v[10:11], v[66:67]
	v_pk_mul_f32 v[58:59], v[58:59], v[66:67]
	v_pk_mul_f32 v[42:43], v[42:43], v[66:67]
	v_pk_mul_f32 v[26:27], v[26:27], v[66:67]
	s_waitcnt lgkmcnt(0)
	v_rcp_f32_e32 v66, v70
	v_rcp_f32_e32 v67, v71
	v_pk_mul_f32 v[12:13], v[12:13], v[68:69]
	v_pk_mul_f32 v[60:61], v[60:61], v[68:69]
	v_pk_mul_f32 v[44:45], v[44:45], v[68:69]
	v_pk_mul_f32 v[14:15], v[14:15], v[66:67]
	v_pk_mul_f32 v[62:63], v[62:63], v[66:67]
	v_pk_mul_f32 v[46:47], v[46:47], v[66:67]
	v_pk_mul_f32 v[30:31], v[30:31], v[66:67]
	v_lshrrev_b32_e32 v252, 6, v1
	v_pk_mul_f32 v[28:29], v[28:29], v[68:69]
	v_rcp_f32_e32 v68, v72
	v_rcp_f32_e32 v69, v73
	v_pk_mul_f32 v[8:9], v[8:9], v[74:75]
	v_and_b32_e32 v253, 63, v1
	v_lshlrev_b32_e32 v252, 14, v252
	v_lshl_add_u32 v252, v253, 4, v252
	v_add_u32_e32 v253, 0x1000, v252
	v_add_u32_e32 v254, 0x2000, v252
	v_add_u32_e32 v255, 0x3000, v252
	v_pk_mul_f32 v[56:57], v[56:57], v[74:75]
	v_pk_mul_f32 v[24:25], v[24:25], v[74:75]
	v_pk_mul_f32 v[16:17], v[16:17], v[68:69]
	v_pk_mul_f32 v[64:65], v[64:65], v[68:69]
	v_pk_mul_f32 v[48:49], v[48:49], v[68:69]
	v_pk_mul_f32 v[32:33], v[32:33], v[68:69]
	global_store_dwordx4 v252, v[2:5], s[16:17]
	global_store_dwordx4 v252, v[6:9], s[16:17] offset:1024
	global_store_dwordx4 v252, v[10:13], s[16:17] offset:2048
	global_store_dwordx4 v252, v[14:17], s[16:17] offset:3072
	global_store_dwordx4 v253, v[50:53], s[16:17]
	global_store_dwordx4 v253, v[54:57], s[16:17] offset:1024
	global_store_dwordx4 v253, v[58:61], s[16:17] offset:2048
	global_store_dwordx4 v253, v[62:65], s[16:17] offset:3072
	global_store_dwordx4 v254, v[34:37], s[16:17]
	global_store_dwordx4 v254, v[38:41], s[16:17] offset:1024
	global_store_dwordx4 v254, v[42:45], s[16:17] offset:2048
	global_store_dwordx4 v254, v[46:49], s[16:17] offset:3072
	global_store_dwordx4 v255, v[18:21], s[16:17]
	global_store_dwordx4 v255, v[22:25], s[16:17] offset:1024
	global_store_dwordx4 v255, v[26:29], s[16:17] offset:2048
	global_store_dwordx4 v255, v[30:33], s[16:17] offset:3072
	v_mov_b32_e32 v40, v1
	v_mov_b32_e32 v5, v191
	v_ashrrev_i32_e32 v42, 6, v40
	v_and_b32_e32 v41, 31, v40
	v_lshl_or_b32 v2, v42, 5, v41
	v_ashrrev_i32_e32 v3, 31, v2
	v_lshlrev_b64 v[2:3], 11, v[2:3]
	v_lshrrev_b32_e32 v4, 1, v40
	v_ashrrev_i32_e32 v26, 4, v40
	v_lshl_add_u64 v[2:3], s[38:39], 0, v[2:3]
	v_and_b32_e32 v190, 16, v4
	v_lshlrev_b32_e32 v50, 3, v40
	v_ashrrev_i32_e32 v27, 31, v26
	v_lshl_add_u64 v[2:3], v[2:3], 0, v[190:191]
	v_and_b32_e32 v4, 0x78, v50
	v_lshlrev_b64 v[34:35], 11, v[26:27]
	global_load_dwordx4 v[130:133], v[2:3], off offset:128
	global_load_dwordx4 v[134:137], v[2:3], off offset:160
	global_load_dwordx4 v[138:141], v[2:3], off offset:192
	global_load_dwordx4 v[142:145], v[2:3], off offset:224
	v_lshl_add_u64 v[2:3], s[34:35], 0, v[34:35]
	v_lshlrev_b32_e32 v4, 1, v4
	v_ashrrev_i32_e32 v30, 3, v40
	v_lshl_add_u64 v[38:39], v[2:3], 0, v[4:5]
	v_ashrrev_i32_e32 v31, 31, v30
	v_add_co_u32_e32 v14, vcc, s62, v38
	v_lshlrev_b32_e32 v51, 4, v40
	v_lshlrev_b64 v[36:37], 11, v[30:31]
	v_addc_co_u32_e32 v15, vcc, 0, v39, vcc
	v_and_b32_e32 v32, 0x70, v51
	v_lshl_add_u64 v[10:11], s[30:31], 0, v[36:37]
	v_mov_b32_e32 v33, v191
	v_add_co_u32_e32 v18, vcc, s63, v38
	v_add_u32_e32 v28, 32, v26
	v_lshl_add_u64 v[44:45], v[10:11], 0, v[32:33]
	v_addc_co_u32_e32 v19, vcc, 0, v39, vcc
	v_ashrrev_i32_e32 v29, 31, v28
	v_add_co_u32_e32 v22, vcc, s62, v44
	v_lshlrev_b64 v[2:3], 11, v[28:29]
	s_nop 0
	v_addc_co_u32_e32 v23, vcc, 0, v45, vcc
	v_lshl_add_u64 v[2:3], s[34:35], 0, v[2:3]
	v_add_co_u32_e32 v46, vcc, s64, v38
	v_lshl_add_u64 v[6:7], v[2:3], 0, v[4:5]
	s_nop 0
	v_addc_co_u32_e32 v47, vcc, 0, v39, vcc
	s_barrier
; #define SLOAD(S, k0) do { vs##S##0 = *reinterpret_cast<const bf16x8*>(&Vh[(size_t)((k0) + sr) * LDK + sc]); \
;     vs##S##1 = *reinterpret_cast<const bf16x8*>(&Vh[(size_t)((k0) + 32 + sr) * LDK + sc]); \
;     ks##S = *reinterpret_cast<const bf16x8*>(&Kh[(size_t)((k0) + kr) * LDK + kc]); } while (0)
; #define SWRITE(b, S) do { *(bf16x8*)(V_lds + (b) * SHM_V + vst0) = vs##S##0; *(bf16x8*)(V_lds + (b) * SHM_V + vst1) = vs##S##1; \
;     *(bf16x8*)(K_lds + (b) * SHM_K + kst) = ks##S; } while (0)
; __device__ __forceinline__ void attn_stream(const u16* __restrict__ Qb, const u16* __restrict__ Kh, const u16* __restrict__ Vh,
;                                             int seq, char* lds, f32x16 (&o)[4]) {
;     ...
;   f32x16 p0, p1; float al; bf16x8 pa0, pa1, pa2, pa3; const int NT = seq / 64;
;     ...
;   const bool late = wid >= 4;
;   __syncthreads();
;   SLOAD(A, 0); SLOAD(B, 64); asm volatile("s_waitcnt vmcnt(0)" ::: "memory"); SWRITE(0, A); SWRITE(1, B);
;   SLOAD(A, 128); SLOAD(B, 192);
;   __syncthreads();
	global_load_dwordx4 v[2:5], v[38:39], off
	s_nop 0
	global_load_dwordx4 v[6:9], v[6:7], off
	s_nop 0
	global_load_dwordx4 v[10:13], v[44:45], off offset:128
	s_nop 0
	global_load_dwordx4 v[14:17], v[14:15], off
	s_nop 0
	global_load_dwordx4 v[18:21], v[18:19], off
	s_nop 0
	global_load_dwordx4 v[22:25], v[22:23], off offset:128
	v_add_co_u32_e32 v48, vcc, s65, v38
	s_waitcnt vmcnt(0)
	v_and_b32_e32 v27, 0x3fffffc0, v40
	s_nop 0
	v_addc_co_u32_e32 v49, vcc, 0, v39, vcc
	global_load_dwordx4 v[146:149], v[46:47], off
	global_load_dwordx4 v[150:153], v[48:49], off
	v_add_co_u32_e32 v46, vcc, s64, v44
	v_lshl_add_u32 v204, v27, 2, s84
	s_nop 0
	v_addc_co_u32_e32 v47, vcc, 0, v45, vcc
	v_add_co_u32_e32 v48, vcc, s66, v38
	v_and_b32_e32 v27, 0xfffff0, v26
	s_nop 0
	v_addc_co_u32_e32 v49, vcc, 0, v39, vcc
	v_add_co_u32_e32 v38, vcc, s67, v38
	global_load_dwordx4 v[158:161], v[46:47], off offset:128
	global_load_dwordx4 v[154:157], v[48:49], off
	v_addc_co_u32_e32 v39, vcc, 0, v39, vcc
	v_add_co_u32_e32 v44, vcc, s66, v44
	v_lshlrev_b32_e32 v29, 1, v26
	s_nop 0
	v_addc_co_u32_e32 v45, vcc, 0, v45, vcc
	global_load_dwordx4 v[162:165], v[38:39], off
	global_load_dwordx4 v[166:169], v[44:45], off offset:128
	v_and_or_b32 v27, v29, 8, v27
	v_lshrrev_b32_e32 v29, 1, v26
	v_lshrrev_b32_e32 v27, 1, v27
	v_bfe_u32 v31, v50, 5, 2
	v_and_b32_e32 v26, 3, v26
	v_or_b32_e32 v27, v27, v31
	v_and_or_b32 v26, v29, 4, v26
	v_lshlrev_b32_e32 v27, 9, v27
	v_lshlrev_b32_e32 v26, 6, v26
	v_and_b32_e32 v29, 48, v51
	v_or3_b32 v205, v27, v26, v29
	v_and_b32_e32 v27, 0xfffff0, v28
	v_lshlrev_b32_e32 v28, 1, v28
	v_and_or_b32 v27, v28, 8, v27
	v_lshrrev_b32_e32 v27, 1, v27
	v_or_b32_e32 v27, v27, v31
	v_lshlrev_b32_e32 v27, 9, v27
	v_or3_b32 v206, v27, v26, v29
	v_lshlrev_b32_e32 v26, 7, v30
	v_and_b32_e32 v27, 0x70, v40
	v_bitop3_b32 v26, v32, v26, v27 bitop3:0xde
	v_add_u32_e32 v27, 0, v205
	v_add_u32_e32 v207, 0, v26
	v_and_b32_e32 v43, 63, v40
	s_waitcnt vmcnt(11)
	ds_write_b128 v27, v[2:5]
	v_add_u32_e32 v2, 0, v206
	s_waitcnt vmcnt(10)
	ds_write_b128 v2, v[6:9]
	s_waitcnt vmcnt(9)
	ds_write_b128 v207, v[10:13] offset:49152
	s_waitcnt vmcnt(8)
	ds_write_b128 v27, v[14:17] offset:16384
	s_waitcnt vmcnt(7)
	ds_write_b128 v2, v[18:21] offset:16384
	s_waitcnt vmcnt(6)
	ds_write_b128 v207, v[22:25] offset:57344
	v_lshlrev_b32_e32 v2, 7, v41
	v_and_b32_e32 v3, 0x70, v50
	v_or_b32_e32 v4, 32, v190
	v_bitop3_b32 v209, v4, v2, v3 bitop3:0xde
	v_or_b32_e32 v4, 64, v190
	v_bitop3_b32 v208, v190, v2, v3 bitop3:0xde
	v_bitop3_b32 v210, v4, v2, v3 bitop3:0xde
	v_or_b32_e32 v4, 0x60, v190
	v_add_u32_e32 v6, 0, v208
	v_bitop3_b32 v211, v4, v2, v3 bitop3:0xde
	s_waitcnt lgkmcnt(0)
	s_barrier
; __device__ __forceinline__ void partialSM(f32x16& p0, f32x16& p1, float& m_reg, f32x16& negm, float& alpha, const bool first) {
;   constexpr float THR = 8.f * 1.4426950408889634f;
;   float pmax = p0[0];
; #pragma unroll
;   for (int r = 1; r < 16; ++r) pmax = fmaxf(pmax, p0[r]);
; #pragma unroll
;   for (int r = 0; r < 16; ++r) pmax = fmaxf(pmax, p1[r]);
;   { auto rr = __builtin_amdgcn_permlane32_swap(__float_as_uint(pmax), __float_as_uint(pmax), false, false);
;     pmax = fmaxf(__uint_as_float(rr[0]), __uint_as_float(rr[1])); }
;   if (__builtin_expect(!first && __all(pmax <= THR), 1)) { alpha = 1.f; }
;   else {
;     const float sh = first ? pmax : fmaxf(pmax, 0.f);
;     alpha = __builtin_amdgcn_exp2f(-sh); m_reg += sh;
; #pragma unroll
;     for (int r = 0; r < 16; ++r) { p0[r] -= sh; p1[r] -= sh; }
;     const float nm = -m_reg;
; #pragma unroll
;     for (int r = 0; r < 16; ++r) negm[r] = nm;
;   }
; #pragma unroll
;   for (int r = 0; r < 16; ++r) p0[r] = __builtin_amdgcn_exp2f(p0[r]);
; }
; __device__ __forceinline__ void finishSM(f32x16& p0, f32x16& p1, float alpha, float& l_reg, bf16x8& pa0, bf16x8& pa1, bf16x8& pa2, bf16x8& pa3) {
; #pragma unroll
;   for (int r = 0; r < 16; ++r) p1[r] = __builtin_amdgcn_exp2f(p1[r]);
;   float ps = 0;
; #pragma unroll
;   for (int r = 0; r < 16; ++r) ps += p0[r];
; #pragma unroll
;   for (int r = 0; r < 16; ++r) ps += p1[r];
;   { auto rr = __builtin_amdgcn_permlane32_swap(__float_as_uint(ps), __float_as_uint(ps), false, false);
;     ps = __uint_as_float(rr[0]) + __uint_as_float(rr[1]); }
;   l_reg = l_reg * alpha + ps;
;     ...
;   PK4(p0, 0, pa0); PK4(p0, 8, pa1); PK4(p1, 0, pa2); PK4(p1, 8, pa3);
;     ...
; }
; __device__ __forceinline__ void qkt(f32x16& p0, f32x16& p1, const char* Ks, const bf16x8* qr, int r32, int hi, const f32x16& negm) {
;     ...
;   p0 = __builtin_amdgcn_mfma_f32_32x32x16_bf16(ka[0], qr[0], negm, 0, 0, 0);
;   p0 = __builtin_amdgcn_mfma_f32_32x32x16_bf16(ka[1], qr[1], p0, 0, 0, 0);
;   p0 = __builtin_amdgcn_mfma_f32_32x32x16_bf16(ka[2], qr[2], p0, 0, 0, 0);
;   p0 = __builtin_amdgcn_mfma_f32_32x32x16_bf16(ka[3], qr[3], p0, 0, 0, 0);
;   p1 = __builtin_amdgcn_mfma_f32_32x32x16_bf16(kb[0], qr[0], negm, 0, 0, 0);
;   p1 = __builtin_amdgcn_mfma_f32_32x32x16_bf16(kb[1], qr[1], p1, 0, 0, 0);
;   p1 = __builtin_amdgcn_mfma_f32_32x32x16_bf16(kb[2], qr[2], p1, 0, 0, 0);
	v_add_u32_e32 v7, 0, v209
	v_add_u32_e32 v8, 0, v210
	v_add_u32_e32 v9, 0, v211
	ds_read_b128 v[2:5], v6 offset:49152
	ds_read_b128 v[18:21], v6 offset:53248
	ds_read_b128 v[22:25], v7 offset:49152
	ds_read_b128 v[44:47], v7 offset:53248
	ds_read_b128 v[26:29], v8 offset:49152
	ds_read_b128 v[48:51], v8 offset:53248
	ds_read_b128 v[30:33], v9 offset:49152
	ds_read_b128 v[52:55], v9 offset:53248
	s_waitcnt lgkmcnt(0)
	s_waitcnt lgkmcnt(7)
	s_waitcnt lgkmcnt(6)
	s_waitcnt lgkmcnt(5)
	s_waitcnt lgkmcnt(4)
	s_waitcnt lgkmcnt(3)
	s_waitcnt lgkmcnt(2)
	s_waitcnt lgkmcnt(1)
	s_waitcnt lgkmcnt(0)
	v_mfma_f32_32x32x16_bf16 v[2:17], v[2:5], v[130:133], 0
	v_mfma_f32_32x32x16_bf16 v[2:17], v[22:25], v[134:137], v[2:17]
	v_mfma_f32_32x32x16_bf16 v[2:17], v[26:29], v[138:141], v[2:17]
	v_mfma_f32_32x32x16_bf16 v[2:17], v[30:33], v[142:145], v[2:17]
	v_mfma_f32_32x32x16_bf16 v[18:33], v[18:21], v[130:133], 0
	v_mfma_f32_32x32x16_bf16 v[18:33], v[44:47], v[134:137], v[18:33]
	v_mfma_f32_32x32x16_bf16 v[18:33], v[48:51], v[138:141], v[18:33]
	v_mfma_f32_32x32x16_bf16 v[18:33], v[52:55], v[142:145], v[18:33]
	s_nop 7
	v_max_f32_e32 v38, v3, v3
	v_max_f32_e32 v39, v2, v2
	v_max_f32_e32 v38, v39, v38
	v_max3_f32 v38, v38, v4, v5
	v_max3_f32 v38, v38, v6, v7
	v_max3_f32 v38, v38, v8, v9
	v_max3_f32 v38, v38, v10, v11
	v_max3_f32 v38, v38, v12, v13
	v_max3_f32 v38, v38, v14, v15
	v_max3_f32 v38, v38, v16, v17
	v_max3_f32 v38, v38, v18, v19
	v_max3_f32 v38, v38, v20, v21
	v_max3_f32 v38, v38, v22, v23
	v_max3_f32 v38, v38, v24, v25
	v_max3_f32 v38, v38, v26, v27
	v_max3_f32 v38, v38, v28, v29
	v_max3_f32 v38, v38, v30, v31
	v_max3_f32 v38, v38, v32, v33
	v_mov_b32_e32 v39, v38
	s_nop 1
	v_permlane32_swap_b32_e32 v38, v39
	v_max_f32_e32 v39, v39, v39
	v_max_f32_e32 v38, v38, v38
	v_max_f32_e32 v39, v38, v39
	v_sub_f32_e32 v2, v2, v39
	v_sub_f32_e32 v3, v3, v39
	v_exp_f32_e32 v2, v2
	v_sub_f32_e32 v4, v4, v39
	v_exp_f32_e32 v3, v3
	v_sub_f32_e32 v5, v5, v39
	v_exp_f32_e32 v4, v4
	v_sub_f32_e32 v18, v18, v39
	v_sub_f32_e32 v6, v6, v39
	v_exp_f32_e32 v5, v5
	v_sub_f32_e32 v7, v7, v39
	v_exp_f32_e32 v6, v6
	v_exp_f32_e32 v38, v18
	v_add_f32_e32 v18, 0, v2
	v_sub_f32_e32 v8, v8, v39
	v_exp_f32_e32 v7, v7
	v_add_f32_e32 v18, v3, v18
	v_sub_f32_e32 v9, v9, v39
	v_exp_f32_e32 v8, v8
	v_add_f32_e32 v18, v4, v18
	v_sub_f32_e32 v10, v10, v39
	v_exp_f32_e32 v9, v9
	v_add_f32_e32 v18, v5, v18
	v_sub_f32_e32 v11, v11, v39
	v_exp_f32_e32 v10, v10
	v_add_f32_e32 v18, v6, v18
	v_sub_f32_e32 v12, v12, v39
	v_exp_f32_e32 v11, v11
	v_add_f32_e32 v18, v7, v18
	v_sub_f32_e32 v13, v13, v39
	v_exp_f32_e32 v12, v12
	v_add_f32_e32 v18, v8, v18
	v_sub_f32_e32 v14, v14, v39
	v_exp_f32_e32 v13, v13
	v_add_f32_e32 v18, v9, v18
	v_sub_f32_e32 v15, v15, v39
	v_exp_f32_e32 v14, v14
	v_add_f32_e32 v18, v10, v18
	v_sub_f32_e32 v16, v16, v39
	v_exp_f32_e32 v15, v15
	v_add_f32_e32 v18, v11, v18
	v_sub_f32_e32 v17, v17, v39
	v_exp_f32_e32 v16, v16
	v_add_f32_e32 v18, v12, v18
	v_exp_f32_e32 v17, v17
	v_add_f32_e32 v18, v13, v18
	v_sub_f32_e32 v19, v19, v39
	v_add_f32_e32 v18, v14, v18
	v_sub_f32_e32 v20, v20, v39
	v_exp_f32_e32 v45, v19
	v_add_f32_e32 v18, v15, v18
	v_sub_f32_e32 v21, v21, v39
	v_exp_f32_e32 v20, v20
	v_add_f32_e32 v18, v16, v18
	v_sub_f32_e32 v22, v22, v39
	v_exp_f32_e32 v21, v21
	v_add_f32_e32 v18, v17, v18
	v_sub_f32_e32 v23, v23, v39
	v_exp_f32_e32 v22, v22
	v_add_f32_e32 v18, v38, v18
	v_sub_f32_e32 v24, v24, v39
	v_exp_f32_e32 v23, v23
	v_add_f32_e32 v18, v45, v18
	v_sub_f32_e32 v25, v25, v39
	v_exp_f32_e32 v24, v24
	v_add_f32_e32 v18, v20, v18
	v_sub_f32_e32 v26, v26, v39
	v_exp_f32_e32 v25, v25
	v_add_f32_e32 v18, v21, v18
	v_sub_f32_e32 v27, v27, v39
	v_exp_f32_e32 v26, v26
	v_add_f32_e32 v18, v22, v18
	v_sub_f32_e32 v28, v28, v39
	v_exp_f32_e32 v27, v27
	v_add_f32_e32 v18, v23, v18
	v_sub_f32_e32 v29, v29, v39
	v_exp_f32_e32 v28, v28
	v_add_f32_e32 v18, v24, v18
	v_sub_f32_e32 v30, v30, v39
	v_exp_f32_e32 v29, v29
	v_add_f32_e32 v18, v25, v18
	v_sub_f32_e32 v31, v31, v39
	v_exp_f32_e32 v30, v30
	v_add_f32_e32 v18, v26, v18
	v_sub_f32_e32 v32, v32, v39
	v_exp_f32_e32 v31, v31
	v_add_f32_e32 v18, v27, v18
	v_sub_f32_e32 v33, v33, v39
	v_exp_f32_e32 v32, v32
	v_add_f32_e32 v18, v28, v18
	v_exp_f32_e32 v33, v33
	v_add_f32_e32 v18, v29, v18
	v_add_f32_e32 v18, v30, v18
	v_exp_f32_e64 v44, -v39
	v_add_f32_e32 v18, v31, v18
	v_add_f32_e32 v18, v32, v18
	v_add_f32_e32 v18, v33, v18
	v_mov_b32_e32 v19, v18
	s_nop 0
	v_cvt_pk_bf16_f32 v170, v2, v3
	s_nop 0
	v_cvt_pk_bf16_f32 v171, v4, v5
	s_nop 0
	v_cvt_pk_bf16_f32 v172, v6, v7
	s_nop 0
	v_cvt_pk_bf16_f32 v173, v8, v9
	s_nop 0
	v_cvt_pk_bf16_f32 v174, v10, v11
	s_nop 0
	v_cvt_pk_bf16_f32 v175, v12, v13
	s_nop 0
	v_cvt_pk_bf16_f32 v176, v14, v15
	s_nop 0
	v_cvt_pk_bf16_f32 v177, v16, v17
	s_nop 0
	v_cvt_pk_bf16_f32 v178, v38, v45
	s_nop 0
	v_cvt_pk_bf16_f32 v179, v20, v21
	s_nop 0
	v_cvt_pk_bf16_f32 v180, v22, v23
	s_nop 0
	v_cvt_pk_bf16_f32 v181, v24, v25
	s_nop 0
	v_cvt_pk_bf16_f32 v182, v26, v27
	s_nop 0
	v_cvt_pk_bf16_f32 v183, v28, v29
	s_nop 0
	v_cvt_pk_bf16_f32 v184, v30, v31
	s_nop 0
	v_cvt_pk_bf16_f32 v185, v32, v33
	s_nop 1
	v_permlane32_swap_b32_e32 v18, v19
	v_permlane32_swap_b32_e32 v170, v172
	v_permlane32_swap_b32_e32 v171, v173
	v_permlane32_swap_b32_e32 v174, v176
	v_permlane32_swap_b32_e32 v175, v177
	v_permlane32_swap_b32_e32 v178, v180
	v_permlane32_swap_b32_e32 v179, v181
	v_permlane32_swap_b32_e32 v182, v184
	v_permlane32_swap_b32_e32 v183, v185
	v_cmp_gt_f32_e32 vcc, 1.0, v44
	v_cmp_gt_u32_e64 s[0:1], 32, v43
	s_cbranch_vccz .LBB0_367
	s_and_saveexec_b64 s[4:5], s[0:1]
	v_lshl_add_u32 v2, v41, 2, v204
	ds_write_b32 v2, v44 offset:128
	s_or_b64 exec, exec, s[4:5]
	s_waitcnt lgkmcnt(0)
	v_add_u32_e32 v10, v204, v190
	ds_read_b128 v[2:5], v10 offset:224
	ds_read_b128 v[6:9], v10 offset:192
	ds_read_b128 v[20:23], v10 offset:160
	ds_read_b128 v[24:27], v10 offset:128
	s_waitcnt lgkmcnt(3)
	v_pk_mul_f32 v[16:17], v[4:5], 0 op_sel_hi:[1,0]
	s_waitcnt lgkmcnt(2)
	v_pk_mul_f32 v[12:13], v[8:9], 0 op_sel_hi:[1,0]
	s_waitcnt lgkmcnt(1)
	v_pk_mul_f32 v[8:9], v[22:23], 0 op_sel_hi:[1,0]
	s_waitcnt lgkmcnt(0)
	v_pk_mul_f32 v[4:5], v[26:27], 0 op_sel_hi:[1,0]
	v_pk_mul_f32 v[14:15], v[2:3], 0 op_sel_hi:[1,0]
	v_pk_mul_f32 v[10:11], v[6:7], 0 op_sel_hi:[1,0]
	v_pk_mul_f32 v[6:7], v[20:21], 0 op_sel_hi:[1,0]
	v_pk_mul_f32 v[2:3], v[24:25], 0 op_sel_hi:[1,0]
	s_branch .LBB0_368

; __device__ __forceinline__ u16 f2bf(float f) { return (u16)(cvtpk(f, f) & 0xffffu); }
; __device__ __forceinline__ int opq(int x) { asm volatile("" : "+v"(x)); return x; }
; __device__ __forceinline__ void phase3(const Params& p, char* shm) {
;     ...
;     __syncthreads();
;     const int tid = opq((int)threadIdx.x), wid = tid >> 6, lane = tid & 63, r32 = lane & 31, hi = lane >> 5;
;     { const f32x4* o1p = reinterpret_cast<const f32x4*>(o1s + tid * 64);
; #pragma unroll
;       for (int d0 = 0; d0 < 4; ++d0)
; #pragma unroll
;         for (int q = 0; q < 4; ++q) { const f32x4 v1 = o1p[d0 * 4 + q];
; #pragma unroll
;           for (int e = 0; e < 4; ++e) o[d0][q * 4 + e] = v1[e] - lam * o[d0][q * 4 + e]; } }
;     float sw[4];
; #pragma unroll
;     for (int d0 = 0; d0 < 4; ++d0) sw[d0] = p.subln[d0 * 32 + r32] * 0.8f;
;     char* const otb = shm + ((wid * 32 + 4 * hi) * OT_LD + r32) * 2;
; #pragma unroll
;     for (int r = 0; r < 16; ++r) {
;       float ss = 0.f;
; #pragma unroll
;       for (int d0 = 0; d0 < 4; ++d0) ss += o[d0][r] * o[d0][r];
;       ss += __shfl_xor(ss, 1); ss += __shfl_xor(ss, 2); ss += __shfl_xor(ss, 4); ss += __shfl_xor(ss, 8); ss += __shfl_xor(ss, 16);
;       const float rstd = rsqrtf(ss * (1.f / 128.f) + 1e-6f);
; #pragma unroll
;       for (int d0 = 0; d0 < 4; ++d0) *(u16*)(otb + (((r & 3) + 8 * (r >> 2)) * OT_LD + d0 * 32) * 2) = f2bf(o[d0][r] * rstd * sw[d0]);
;     }
.LBB0_401:
	s_or_b64 exec, exec, s[6:7]
	s_and_saveexec_b64 s[0:1], s[4:5]
	ds_write_b32 v212, v192
	s_or_b64 exec, exec, s[0:1]
	s_waitcnt lgkmcnt(0)
	v_add_u32_e32 v66, v204, v190
	v_mov_b32_e32 v131, v1
	ds_read_b128 v[138:141], v66
	s_waitcnt vmcnt(2)
	ds_read_b128 v[144:147], v66 offset:32
	s_waitcnt vmcnt(1)
	ds_read_b128 v[148:151], v66 offset:64
	ds_read_b128 v[152:155], v66 offset:96
	s_waitcnt lgkmcnt(0)
	s_barrier
	v_mov_b32_e32 v156, v2
	v_lshrrev_b32_e32 v252, 6, v131
	v_and_b32_e32 v253, 63, v131
	v_lshlrev_b32_e32 v252, 14, v252
	v_lshl_add_u32 v252, v253, 4, v252
	v_add_u32_e32 v253, 0x1000, v252
	v_add_u32_e32 v254, 0x2000, v252
	v_add_u32_e32 v255, 0x3000, v252
	global_load_dwordx4 v[118:121], v252, s[16:17]
	global_load_dwordx4 v[126:129], v253, s[16:17]
	global_load_dwordx4 v[114:117], v254, s[16:17]
	global_load_dwordx4 v[122:125], v255, s[16:17]
	global_load_dwordx4 v[110:113], v252, s[16:17] offset:1024
	global_load_dwordx4 v[106:109], v253, s[16:17] offset:1024
	global_load_dwordx4 v[102:105], v254, s[16:17] offset:1024
	global_load_dwordx4 v[98:101], v255, s[16:17] offset:1024
	v_and_b32_e32 v143, 31, v131
	v_lshlrev_b32_e32 v68, 2, v143
	global_load_dword v161, v68, s[14:15]
	global_load_dword v163, v68, s[14:15] offset:128
	v_and_b32_e32 v67, 64, v203
	v_xor_b32_e32 v66, 1, v203
	v_add_u32_e32 v2, 64, v67
	v_xor_b32_e32 v69, 2, v203
	v_cmp_lt_i32_e32 vcc, v66, v2
	v_xor_b32_e32 v70, 4, v203
	s_waitcnt vmcnt(10)
	v_mov_b32_e32 v159, v18
	v_mov_b32_e32 v18, v35
	v_cndmask_b32_e32 v35, v203, v66, vcc
	v_cmp_lt_i32_e32 vcc, v69, v2
	global_load_dword v165, v68, s[14:15] offset:256
	global_load_dword v168, v68, s[14:15] offset:384
	v_xor_b32_e32 v68, 8, v203
	v_cndmask_b32_e32 v66, v203, v69, vcc
	v_cmp_lt_i32_e32 vcc, v70, v2
	v_xor_b32_e32 v71, 16, v203
	v_mov_b32_e32 v157, v50
	v_cndmask_b32_e32 v67, v203, v70, vcc
	v_cmp_lt_i32_e32 vcc, v68, v2
	v_mov_b32_e32 v50, v3
	v_lshrrev_b32_e32 v3, 3, v131
	v_cndmask_b32_e32 v68, v203, v68, vcc
	v_cmp_lt_i32_e32 vcc, v71, v2
	v_mov_b32_e32 v158, v34
	v_lshrrev_b32_e32 v34, 1, v131
	v_cndmask_b32_e32 v2, v203, v71, vcc
	v_and_b32_e32 v69, 4, v3
	v_lshlrev_b32_e32 v3, 2, v2
	v_and_or_b32 v2, v34, s69, v69
	v_mul_lo_u32 v169, v2, s70
	v_rcp_f32_e32 v2, v138
	v_rcp_f32_e32 v162, v140
	v_rcp_f32_e32 v140, v146
	v_rcp_f32_e32 v138, v147
	v_pk_mul_f32 v[146:147], v[156:157], v[2:3] op_sel_hi:[1,0]
	v_pk_mul_f32 v[156:157], v[158:159], v[2:3] op_sel_hi:[1,0]
	v_lshlrev_b32_e32 v137, 2, v35
	v_lshlrev_b32_e32 v135, 2, v66
	v_lshlrev_b32_e32 v133, 2, v67
	v_lshlrev_b32_e32 v35, 2, v68
	v_rcp_f32_e32 v164, v141
	v_rcp_f32_e32 v160, v139
	v_or_b32_e32 v139, v169, v143
	v_rcp_f32_e32 v136, v148
	v_rcp_f32_e32 v134, v149
	v_rcp_f32_e32 v132, v150
	v_rcp_f32_e32 v130, v151
	global_load_dwordx4 v[74:77], v252, s[16:17] offset:3072
	global_load_dwordx4 v[90:93], v252, s[16:17] offset:2048
	global_load_dwordx4 v[78:81], v253, s[16:17] offset:3072
	global_load_dwordx4 v[94:97], v253, s[16:17] offset:2048
	global_load_dwordx4 v[66:69], v254, s[16:17] offset:3072
	global_load_dwordx4 v[82:85], v254, s[16:17] offset:2048
	global_load_dwordx4 v[70:73], v255, s[16:17] offset:3072
	s_nop 0
	global_load_dwordx4 v[86:89], v255, s[16:17] offset:2048
	v_rcp_f32_e32 v144, v144
	v_rcp_f32_e32 v142, v145
	s_waitcnt vmcnt(19)
	v_mov_b32_e32 v158, v118
	s_waitcnt vmcnt(18)
	v_mov_b32_e32 v159, v126
	s_waitcnt vmcnt(17)
	v_mov_b32_e32 v166, v114
	s_waitcnt vmcnt(16)
	v_mov_b32_e32 v167, v122
	v_pk_fma_f32 v[146:147], v[188:189], v[146:147], v[158:159] neg_lo:[1,0,0] neg_hi:[1,0,0]
	v_pk_fma_f32 v[156:157], v[188:189], v[156:157], v[166:167] neg_lo:[1,0,0] neg_hi:[1,0,0]
	v_pk_mul_f32 v[158:159], v[146:147], v[146:147]
	v_pk_mul_f32 v[166:167], v[156:157], v[156:157]
	v_add_f32_e32 v2, v158, v159
	v_add_f32_e32 v2, v2, v166
	v_add_f32_e32 v2, v2, v167
	ds_bpermute_b32 v34, v137, v2
	s_waitcnt vmcnt(11)
	v_pk_mul_f32 v[148:149], v[50:51], v[160:161] op_sel_hi:[1,0]
	v_pk_mul_f32 v[150:151], v[18:19], v[160:161] op_sel_hi:[1,0]
	v_mul_f32_e32 v51, 0x3f4ccccd, v161
	v_rcp_f32_e32 v118, v152
	s_waitcnt lgkmcnt(0)
	v_add_f32_e32 v122, v2, v34
	ds_bpermute_b32 v126, v135, v122
	v_rcp_f32_e32 v114, v153
	v_mov_b32_e32 v152, v116
	v_mov_b32_e32 v153, v124
	s_waitcnt vmcnt(10)
	v_mul_f32_e32 v50, 0x3f4ccccd, v163
	s_waitcnt lgkmcnt(0)
	v_add_f32_e32 v122, v122, v126
	ds_bpermute_b32 v126, v133, v122
	s_waitcnt vmcnt(9)
	v_mul_f32_e32 v19, 0x3f4ccccd, v165
	s_waitcnt vmcnt(8)
	v_mul_f32_e32 v18, 0x3f4ccccd, v168
	v_mov_b32_e32 v124, v117
	v_mov_b32_e32 v117, v22
	s_waitcnt lgkmcnt(0)
	v_add_f32_e32 v141, v122, v126
	ds_bpermute_b32 v143, v35, v141
	v_mov_b32_e32 v122, v115
	v_mov_b32_e32 v126, v119
	v_pk_fma_f32 v[126:127], v[188:189], v[148:149], v[126:127] neg_lo:[1,0,0] neg_hi:[1,0,0]
	v_pk_fma_f32 v[122:123], v[188:189], v[150:151], v[122:123] neg_lo:[1,0,0] neg_hi:[1,0,0]
	s_waitcnt lgkmcnt(0)
	v_add_f32_e32 v115, v141, v143
	ds_bpermute_b32 v119, v3, v115
	v_pk_mul_f32 v[148:149], v[126:127], v[126:127]
	v_pk_mul_f32 v[150:151], v[122:123], v[122:123]
	v_rcp_f32_e32 v34, v154
	v_rcp_f32_e32 v2, v155
	s_waitcnt lgkmcnt(0)
	v_add_f32_e32 v115, v115, v119
	v_add_f32_e32 v119, v148, v149
	v_add_f32_e32 v119, v119, v150
	v_add_f32_e32 v119, v119, v151
	v_fmamk_f32 v115, v115, 0x3c000000, v187
	ds_bpermute_b32 v141, v137, v119
	v_mul_f32_e32 v143, 0x4b800000, v115
	v_cmp_gt_f32_e32 vcc, s71, v115
	v_mov_b32_e32 v148, v120
	v_mov_b32_e32 v149, v128
	v_cndmask_b32_e32 v115, v115, v143, vcc
	v_rsq_f32_e32 v143, v115
	s_waitcnt lgkmcnt(0)
; __device__ __forceinline__ u16 f2bf(float f) { return (u16)(cvtpk(f, f) & 0xffffu); }
; __device__ __forceinline__ void phase3(const Params& p, char* shm) {
;     ...
;         for (int q = 0; q < 4; ++q) { const f32x4 v1 = o1p[d0 * 4 + q];
; #pragma unroll
;           for (int e = 0; e < 4; ++e) o[d0][q * 4 + e] = v1[e] - lam * o[d0][q * 4 + e]; } }
;     float sw[4];
; #pragma unroll
;     for (int d0 = 0; d0 < 4; ++d0) sw[d0] = p.subln[d0 * 32 + r32] * 0.8f;
;     char* const otb = shm + ((wid * 32 + 4 * hi) * OT_LD + r32) * 2;
; #pragma unroll
;     for (int r = 0; r < 16; ++r) {
;       float ss = 0.f;
; #pragma unroll
;       for (int d0 = 0; d0 < 4; ++d0) ss += o[d0][r] * o[d0][r];
;       ss += __shfl_xor(ss, 1); ss += __shfl_xor(ss, 2); ss += __shfl_xor(ss, 4); ss += __shfl_xor(ss, 8); ss += __shfl_xor(ss, 16);
;       const float rstd = rsqrtf(ss * (1.f / 128.f) + 1e-6f);
; #pragma unroll
;       for (int d0 = 0; d0 < 4; ++d0) *(u16*)(otb + (((r & 3) + 8 * (r >> 2)) * OT_LD + d0 * 32) * 2) = f2bf(o[d0][r] * rstd * sw[d0]);
;     }
	v_add_f32_e32 v119, v119, v141
	ds_bpermute_b32 v141, v135, v119
	v_lshl_add_u32 v115, v139, 1, 0
	v_mul_f32_e32 v139, 0x45800000, v143
	v_cndmask_b32_e32 v139, v143, v139, vcc
	v_mul_f32_e32 v143, v146, v139
	v_mul_f32_e32 v143, v51, v143
	s_waitcnt lgkmcnt(0)
	v_add_f32_e32 v119, v119, v141
	s_nop 0
	v_cvt_pk_bf16_f32 v143, v143, v143
	ds_bpermute_b32 v141, v133, v119
	ds_write_b16 v115, v143
	v_mul_f32_e32 v143, v147, v139
	v_mov_b32_e32 v146, v4
	v_mov_b32_e32 v147, v52
	v_pk_mul_f32 v[146:147], v[146:147], v[162:163] op_sel_hi:[1,0]
	v_mov_b32_e32 v150, v36
	v_mov_b32_e32 v151, v20
	v_pk_fma_f32 v[146:147], v[188:189], v[146:147], v[148:149] neg_lo:[1,0,0] neg_hi:[1,0,0]
	v_pk_mul_f32 v[150:151], v[150:151], v[162:163] op_sel_hi:[1,0]
	v_pk_mul_f32 v[148:149], v[146:147], v[146:147]
	v_pk_fma_f32 v[150:151], v[188:189], v[150:151], v[152:153] neg_lo:[1,0,0] neg_hi:[1,0,0]
	v_add_f32_e32 v4, v148, v149
	v_pk_mul_f32 v[152:153], v[150:151], v[150:151]
	s_waitcnt lgkmcnt(1)
	v_add_f32_e32 v119, v119, v141
	v_add_f32_e32 v4, v4, v152
	ds_bpermute_b32 v141, v35, v119
	v_add_f32_e32 v4, v4, v153
	ds_bpermute_b32 v20, v137, v4
	v_mul_f32_e32 v143, v50, v143
	s_nop 0
	v_cvt_pk_bf16_f32 v143, v143, v143
	s_waitcnt lgkmcnt(1)
	v_add_f32_e32 v119, v119, v141
	ds_bpermute_b32 v141, v3, v119
	s_waitcnt lgkmcnt(1)
	v_add_f32_e32 v4, v4, v20
	ds_bpermute_b32 v20, v135, v4
	ds_write_b16 v115, v143 offset:64
	v_mul_f32_e32 v143, v156, v139
	s_waitcnt lgkmcnt(2)
	v_add_f32_e32 v119, v119, v141
	v_fmamk_f32 v119, v119, 0x3c000000, v187
	s_waitcnt lgkmcnt(1)
	v_add_f32_e32 v4, v4, v20
	v_mul_f32_e32 v141, 0x4b800000, v119
	v_cmp_gt_f32_e32 vcc, s71, v119
	ds_bpermute_b32 v20, v133, v4
	v_mul_f32_e32 v139, v157, v139
	v_cndmask_b32_e32 v119, v119, v141, vcc
	v_rsq_f32_e32 v119, v119
	v_mul_f32_e32 v143, v19, v143
	v_mul_f32_e32 v36, v18, v139
	s_nop 0
	v_cvt_pk_bf16_f32 v143, v143, v143
	ds_write_b16 v115, v143 offset:128
	s_nop 0
	v_cvt_pk_bf16_f32 v36, v36, v36
	s_waitcnt lgkmcnt(1)
	v_add_f32_e32 v4, v4, v20
	ds_write_b16 v115, v36 offset:192
	v_mul_f32_e32 v36, 0x45800000, v119
	ds_bpermute_b32 v20, v35, v4
	v_cndmask_b32_e32 v36, v119, v36, vcc
	v_mul_f32_e32 v52, v126, v36
	v_mul_f32_e32 v52, v51, v52
	s_nop 0
	v_cvt_pk_bf16_f32 v52, v52, v52
	ds_write_b16 v115, v52 offset:272
	v_mul_f32_e32 v52, v127, v36
	s_waitcnt lgkmcnt(1)
	v_add_f32_e32 v4, v4, v20
	v_mul_f32_e32 v52, v50, v52
	ds_bpermute_b32 v20, v3, v4
	s_nop 0
	v_cvt_pk_bf16_f32 v52, v52, v52
	ds_write_b16 v115, v52 offset:336
	v_mul_f32_e32 v52, v122, v36
	v_mul_f32_e32 v52, v19, v52
	s_nop 0
	v_cvt_pk_bf16_f32 v52, v52, v52
	ds_write_b16 v115, v52 offset:400
	s_waitcnt lgkmcnt(2)
	v_add_f32_e32 v4, v4, v20
	v_mov_b32_e32 v52, v5
	v_fmamk_f32 v119, v4, 0x3c000000, v187
	v_pk_mul_f32 v[4:5], v[52:53], v[164:165] op_sel_hi:[1,0]
	v_mov_b32_e32 v128, v121
	v_mov_b32_e32 v20, v37
	v_mul_f32_e32 v36, v123, v36
	v_pk_fma_f32 v[4:5], v[188:189], v[4:5], v[128:129] neg_lo:[1,0,0] neg_hi:[1,0,0]
	v_pk_mul_f32 v[20:21], v[20:21], v[164:165] op_sel_hi:[1,0]
	v_mul_f32_e32 v36, v18, v36
	v_pk_mul_f32 v[52:53], v[4:5], v[4:5]
	v_pk_fma_f32 v[20:21], v[188:189], v[20:21], v[124:125] neg_lo:[1,0,0] neg_hi:[1,0,0]
	s_nop 0
	v_cvt_pk_bf16_f32 v116, v36, v36
	v_add_f32_e32 v52, v52, v53
	v_pk_mul_f32 v[36:37], v[20:21], v[20:21]
	v_cmp_gt_f32_e32 vcc, s71, v119
	v_add_f32_e32 v36, v52, v36
	v_add_f32_e32 v36, v36, v37
	ds_bpermute_b32 v37, v137, v36
	v_mul_f32_e32 v52, 0x4b800000, v119
	v_cndmask_b32_e32 v52, v119, v52, vcc
	v_rsq_f32_e32 v52, v52
	ds_write_b16 v115, v116 offset:464
	s_waitcnt lgkmcnt(1)
	v_add_f32_e32 v36, v36, v37
	ds_bpermute_b32 v37, v135, v36
	v_mul_f32_e32 v53, 0x45800000, v52
	v_cndmask_b32_e32 v52, v52, v53, vcc
	v_mul_f32_e32 v53, v146, v52
	v_mul_f32_e32 v53, v51, v53
	s_waitcnt lgkmcnt(0)
	v_add_f32_e32 v36, v36, v37
	ds_bpermute_b32 v37, v133, v36
	s_nop 0
	v_cvt_pk_bf16_f32 v53, v53, v53
	ds_write_b16 v115, v53 offset:544
	v_mul_f32_e32 v53, v147, v52
	v_mul_f32_e32 v53, v50, v53
	s_waitcnt lgkmcnt(1)
	v_add_f32_e32 v36, v36, v37
	ds_bpermute_b32 v37, v35, v36
	s_nop 0
	v_cvt_pk_bf16_f32 v53, v53, v53
	ds_write_b16 v115, v53 offset:608
	v_mul_f32_e32 v53, v150, v52
	v_mul_f32_e32 v53, v19, v53
	s_waitcnt lgkmcnt(1)
	v_add_f32_e32 v36, v36, v37
	ds_bpermute_b32 v37, v3, v36
	s_nop 0
	v_cvt_pk_bf16_f32 v53, v53, v53
	ds_write_b16 v115, v53 offset:672
	v_mul_f32_e32 v119, v151, v52
	v_mov_b32_e32 v52, v110
	s_waitcnt lgkmcnt(1)
	v_add_f32_e32 v36, v36, v37
	v_fmamk_f32 v36, v36, 0x3c000000, v187
	v_mul_f32_e32 v37, 0x4b800000, v36
	v_cmp_gt_f32_e32 vcc, s71, v36
	v_mov_b32_e32 v53, v106
	v_mov_b32_e32 v116, v38
	v_cndmask_b32_e32 v36, v36, v37, vcc
	v_rsq_f32_e32 v122, v36
	v_mov_b32_e32 v36, v6
	v_mov_b32_e32 v37, v54
	v_pk_mul_f32 v[36:37], v[36:37], v[144:145] op_sel_hi:[1,0]
	v_pk_mul_f32 v[116:117], v[116:117], v[144:145] op_sel_hi:[1,0]
	v_pk_fma_f32 v[36:37], v[188:189], v[36:37], v[52:53] neg_lo:[1,0,0] neg_hi:[1,0,0]
	v_mov_b32_e32 v120, v102
	v_mov_b32_e32 v121, v98
	v_pk_mul_f32 v[52:53], v[36:37], v[36:37]
	v_pk_fma_f32 v[116:117], v[188:189], v[116:117], v[120:121] neg_lo:[1,0,0] neg_hi:[1,0,0]
	v_add_f32_e32 v6, v52, v53
	v_pk_mul_f32 v[120:121], v[116:117], v[116:117]
	v_mul_f32_e32 v38, v18, v119
	v_add_f32_e32 v6, v6, v120
	v_add_f32_e32 v6, v6, v121
	ds_bpermute_b32 v22, v137, v6
	s_nop 0
	v_cvt_pk_bf16_f32 v38, v38, v38
	ds_write_b16 v115, v38 offset:736
	v_mul_f32_e32 v38, 0x45800000, v122
	v_cndmask_b32_e32 v38, v122, v38, vcc
	s_waitcnt lgkmcnt(1)
	v_add_f32_e32 v6, v6, v22
	ds_bpermute_b32 v22, v135, v6
	v_mul_f32_e32 v4, v4, v38
	v_mul_f32_e32 v4, v51, v4
	s_nop 0
	v_cvt_pk_bf16_f32 v4, v4, v4
	ds_write_b16 v115, v4 offset:816
	s_waitcnt lgkmcnt(1)
; __device__ __forceinline__ u16 f2bf(float f) { return (u16)(cvtpk(f, f) & 0xffffu); }
; __device__ __forceinline__ void phase3(const Params& p, char* shm) {
;     ...
;         for (int q = 0; q < 4; ++q) { const f32x4 v1 = o1p[d0 * 4 + q];
; #pragma unroll
;           for (int e = 0; e < 4; ++e) o[d0][q * 4 + e] = v1[e] - lam * o[d0][q * 4 + e]; } }
;     float sw[4];
; #pragma unroll
;     for (int d0 = 0; d0 < 4; ++d0) sw[d0] = p.subln[d0 * 32 + r32] * 0.8f;
;     char* const otb = shm + ((wid * 32 + 4 * hi) * OT_LD + r32) * 2;
; #pragma unroll
;     for (int r = 0; r < 16; ++r) {
;       float ss = 0.f;
; #pragma unroll
;       for (int d0 = 0; d0 < 4; ++d0) ss += o[d0][r] * o[d0][r];
;       ss += __shfl_xor(ss, 1); ss += __shfl_xor(ss, 2); ss += __shfl_xor(ss, 4); ss += __shfl_xor(ss, 8); ss += __shfl_xor(ss, 16);
;       const float rstd = rsqrtf(ss * (1.f / 128.f) + 1e-6f);
; #pragma unroll
;       for (int d0 = 0; d0 < 4; ++d0) *(u16*)(otb + (((r & 3) + 8 * (r >> 2)) * OT_LD + d0 * 32) * 2) = f2bf(o[d0][r] * rstd * sw[d0]);
;     }
	v_add_f32_e32 v6, v6, v22
	ds_bpermute_b32 v22, v133, v6
	v_mul_f32_e32 v4, v5, v38
	v_mul_f32_e32 v4, v50, v4
	s_nop 0
	v_cvt_pk_bf16_f32 v4, v4, v4
	ds_write_b16 v115, v4 offset:880
	s_waitcnt lgkmcnt(1)
	v_add_f32_e32 v5, v6, v22
	ds_bpermute_b32 v6, v35, v5
	v_mul_f32_e32 v4, v20, v38
	v_mul_f32_e32 v4, v19, v4
	s_nop 0
	v_cvt_pk_bf16_f32 v4, v4, v4
	ds_write_b16 v115, v4 offset:944
	s_waitcnt lgkmcnt(1)
	v_add_f32_e32 v5, v5, v6
	ds_bpermute_b32 v6, v3, v5
	v_mul_f32_e32 v4, v21, v38
	v_mul_f32_e32 v4, v18, v4
	s_nop 0
	v_cvt_pk_bf16_f32 v38, v4, v4
	v_mov_b32_e32 v54, v7
	s_waitcnt lgkmcnt(0)
	v_add_f32_e32 v4, v5, v6
	v_fmamk_f32 v52, v4, 0x3c000000, v187
	v_pk_mul_f32 v[4:5], v[54:55], v[142:143] op_sel_hi:[1,0]
	v_mov_b32_e32 v106, v111
	v_mov_b32_e32 v22, v39
	v_pk_fma_f32 v[4:5], v[188:189], v[4:5], v[106:107] neg_lo:[1,0,0] neg_hi:[1,0,0]
	v_pk_mul_f32 v[20:21], v[22:23], v[142:143] op_sel_hi:[1,0]
	v_mov_b32_e32 v98, v103
	v_pk_mul_f32 v[6:7], v[4:5], v[4:5]
	v_pk_fma_f32 v[20:21], v[188:189], v[20:21], v[98:99] neg_lo:[1,0,0] neg_hi:[1,0,0]
	v_add_f32_e32 v6, v6, v7
	v_pk_mul_f32 v[22:23], v[20:21], v[20:21]
	v_cmp_gt_f32_e32 vcc, s71, v52
	v_add_f32_e32 v6, v6, v22
	v_add_f32_e32 v6, v6, v23
	ds_bpermute_b32 v7, v137, v6
	v_mul_f32_e32 v22, 0x4b800000, v52
	v_cndmask_b32_e32 v22, v52, v22, vcc
	v_rsq_f32_e32 v22, v22
	ds_write_b16 v115, v38 offset:1008
	s_waitcnt lgkmcnt(1)
	v_add_f32_e32 v6, v6, v7
	ds_bpermute_b32 v7, v135, v6
	v_mul_f32_e32 v23, 0x45800000, v22
	v_cndmask_b32_e32 v22, v22, v23, vcc
	v_mul_f32_e32 v23, v36, v22
	v_mul_f32_e32 v23, v51, v23
	s_waitcnt lgkmcnt(0)
	v_add_f32_e32 v6, v6, v7
	ds_bpermute_b32 v7, v133, v6
	s_nop 0
	v_cvt_pk_bf16_f32 v23, v23, v23
	ds_write_b16 v115, v23 offset:2176
	v_mul_f32_e32 v23, v37, v22
	v_mul_f32_e32 v23, v50, v23
	s_waitcnt lgkmcnt(1)
	v_add_f32_e32 v6, v6, v7
	ds_bpermute_b32 v7, v35, v6
	s_nop 0
	v_cvt_pk_bf16_f32 v23, v23, v23
	ds_write_b16 v115, v23 offset:2240
	v_mul_f32_e32 v23, v116, v22
	v_mul_f32_e32 v23, v19, v23
	s_waitcnt lgkmcnt(1)
	v_add_f32_e32 v6, v6, v7
	ds_bpermute_b32 v7, v3, v6
	s_nop 0
	v_cvt_pk_bf16_f32 v23, v23, v23
	ds_write_b16 v115, v23 offset:2304
	v_mul_f32_e32 v52, v117, v22
	v_mov_b32_e32 v22, v112
	s_waitcnt lgkmcnt(1)
	v_add_f32_e32 v6, v6, v7
	v_fmamk_f32 v6, v6, 0x3c000000, v187
	v_mul_f32_e32 v7, 0x4b800000, v6
	v_cmp_gt_f32_e32 vcc, s71, v6
	v_mov_b32_e32 v23, v108
	v_mov_b32_e32 v36, v40
	v_cndmask_b32_e32 v6, v6, v7, vcc
	v_rsq_f32_e32 v53, v6
	v_mov_b32_e32 v6, v8
	v_mov_b32_e32 v7, v56
	v_pk_mul_f32 v[6:7], v[6:7], v[140:141] op_sel_hi:[1,0]
	v_mov_b32_e32 v37, v24
	v_pk_fma_f32 v[6:7], v[188:189], v[6:7], v[22:23] neg_lo:[1,0,0] neg_hi:[1,0,0]
	v_pk_mul_f32 v[36:37], v[36:37], v[140:141] op_sel_hi:[1,0]
	v_mov_b32_e32 v38, v104
	v_mov_b32_e32 v39, v100
	v_pk_mul_f32 v[22:23], v[6:7], v[6:7]
	v_pk_fma_f32 v[36:37], v[188:189], v[36:37], v[38:39] neg_lo:[1,0,0] neg_hi:[1,0,0]
	v_add_f32_e32 v8, v22, v23
	v_pk_mul_f32 v[38:39], v[36:37], v[36:37]
	v_mul_f32_e32 v23, v18, v52
	v_add_f32_e32 v8, v8, v38
	v_add_f32_e32 v8, v8, v39
	ds_bpermute_b32 v22, v137, v8
	s_nop 0
	v_cvt_pk_bf16_f32 v23, v23, v23
	ds_write_b16 v115, v23 offset:2368
	v_mul_f32_e32 v23, 0x45800000, v53
	v_cndmask_b32_e32 v23, v53, v23, vcc
	s_waitcnt lgkmcnt(1)
	v_add_f32_e32 v8, v8, v22
	ds_bpermute_b32 v22, v135, v8
	v_mul_f32_e32 v4, v4, v23
	v_mul_f32_e32 v4, v51, v4
	s_nop 0
	v_cvt_pk_bf16_f32 v4, v4, v4
	ds_write_b16 v115, v4 offset:2448
	s_waitcnt lgkmcnt(1)
	v_add_f32_e32 v8, v8, v22
	ds_bpermute_b32 v22, v133, v8
	v_mul_f32_e32 v4, v5, v23
	v_mul_f32_e32 v4, v50, v4
	s_nop 0
	v_cvt_pk_bf16_f32 v4, v4, v4
	ds_write_b16 v115, v4 offset:2512
	s_waitcnt lgkmcnt(1)
	v_add_f32_e32 v5, v8, v22
	ds_bpermute_b32 v8, v35, v5
	v_mul_f32_e32 v4, v20, v23
	v_mul_f32_e32 v4, v19, v4
	s_nop 0
	v_cvt_pk_bf16_f32 v4, v4, v4
	ds_write_b16 v115, v4 offset:2576
	s_waitcnt lgkmcnt(1)
	v_add_f32_e32 v5, v5, v8
	ds_bpermute_b32 v8, v3, v5
	v_mul_f32_e32 v4, v21, v23
	v_mul_f32_e32 v4, v18, v4
	s_nop 0
	v_cvt_pk_bf16_f32 v38, v4, v4
	v_mov_b32_e32 v56, v9
	s_waitcnt lgkmcnt(0)
	v_add_f32_e32 v4, v5, v8
	v_fmamk_f32 v39, v4, 0x3c000000, v187
	v_pk_mul_f32 v[4:5], v[56:57], v[138:139] op_sel_hi:[1,0]
	v_mov_b32_e32 v108, v113
	v_mov_b32_e32 v24, v41
	v_pk_fma_f32 v[4:5], v[188:189], v[4:5], v[108:109] neg_lo:[1,0,0] neg_hi:[1,0,0]
	v_pk_mul_f32 v[20:21], v[24:25], v[138:139] op_sel_hi:[1,0]
	v_mov_b32_e32 v100, v105
	v_pk_mul_f32 v[8:9], v[4:5], v[4:5]
	v_pk_fma_f32 v[20:21], v[188:189], v[20:21], v[100:101] neg_lo:[1,0,0] neg_hi:[1,0,0]
	v_add_f32_e32 v8, v8, v9
	v_pk_mul_f32 v[22:23], v[20:21], v[20:21]
	v_cmp_gt_f32_e32 vcc, s71, v39
	v_add_f32_e32 v8, v8, v22
	v_add_f32_e32 v8, v8, v23
	ds_bpermute_b32 v9, v137, v8
	v_mul_f32_e32 v22, 0x4b800000, v39
	v_cndmask_b32_e32 v22, v39, v22, vcc
	v_rsq_f32_e32 v22, v22
	ds_write_b16 v115, v38 offset:2640
	s_waitcnt lgkmcnt(1)
	v_add_f32_e32 v8, v8, v9
	ds_bpermute_b32 v9, v135, v8
	v_mul_f32_e32 v23, 0x45800000, v22
	v_cndmask_b32_e32 v22, v22, v23, vcc
	v_mul_f32_e32 v6, v6, v22
	v_mul_f32_e32 v6, v51, v6
	s_waitcnt lgkmcnt(0)
	v_add_f32_e32 v8, v8, v9
	ds_bpermute_b32 v9, v133, v8
	s_nop 0
	v_cvt_pk_bf16_f32 v6, v6, v6
	ds_write_b16 v115, v6 offset:2720
	v_mul_f32_e32 v6, v7, v22
	v_mul_f32_e32 v6, v50, v6
	s_waitcnt lgkmcnt(1)
	v_add_f32_e32 v7, v8, v9
	ds_bpermute_b32 v8, v35, v7
	s_nop 0
	v_cvt_pk_bf16_f32 v6, v6, v6
	ds_write_b16 v115, v6 offset:2784
	v_mul_f32_e32 v6, v36, v22
	v_mul_f32_e32 v6, v19, v6
	s_waitcnt lgkmcnt(1)
	v_add_f32_e32 v7, v7, v8
	ds_bpermute_b32 v8, v3, v7
	s_nop 0
	v_cvt_pk_bf16_f32 v6, v6, v6
	ds_write_b16 v115, v6 offset:2848
	v_mul_f32_e32 v36, v37, v22
	s_waitcnt vmcnt(4)
; __device__ __forceinline__ u16 f2bf(float f) { return (u16)(cvtpk(f, f) & 0xffffu); }
; __device__ __forceinline__ void phase3(const Params& p, char* shm) {
;     ...
;         for (int q = 0; q < 4; ++q) { const f32x4 v1 = o1p[d0 * 4 + q];
; #pragma unroll
;           for (int e = 0; e < 4; ++e) o[d0][q * 4 + e] = v1[e] - lam * o[d0][q * 4 + e]; } }
;     float sw[4];
; #pragma unroll
;     for (int d0 = 0; d0 < 4; ++d0) sw[d0] = p.subln[d0 * 32 + r32] * 0.8f;
;     char* const otb = shm + ((wid * 32 + 4 * hi) * OT_LD + r32) * 2;
; #pragma unroll
;     for (int r = 0; r < 16; ++r) {
;       float ss = 0.f;
; #pragma unroll
;       for (int d0 = 0; d0 < 4; ++d0) ss += o[d0][r] * o[d0][r];
;       ss += __shfl_xor(ss, 1); ss += __shfl_xor(ss, 2); ss += __shfl_xor(ss, 4); ss += __shfl_xor(ss, 8); ss += __shfl_xor(ss, 16);
;       const float rstd = rsqrtf(ss * (1.f / 128.f) + 1e-6f);
; #pragma unroll
;       for (int d0 = 0; d0 < 4; ++d0) *(u16*)(otb + (((r & 3) + 8 * (r >> 2)) * OT_LD + d0 * 32) * 2) = f2bf(o[d0][r] * rstd * sw[d0]);
;     }
	v_mov_b32_e32 v9, v94
	s_waitcnt lgkmcnt(1)
	v_add_f32_e32 v6, v7, v8
	v_fmamk_f32 v6, v6, 0x3c000000, v187
	v_mul_f32_e32 v7, 0x4b800000, v6
	v_cmp_gt_f32_e32 vcc, s71, v6
	v_mov_b32_e32 v8, v90
	v_mov_b32_e32 v22, v42
	v_cndmask_b32_e32 v6, v6, v7, vcc
	v_rsq_f32_e32 v37, v6
	v_mov_b32_e32 v6, v10
	v_mov_b32_e32 v7, v58
	v_pk_mul_f32 v[6:7], v[6:7], v[136:137] op_sel_hi:[1,0]
	v_mov_b32_e32 v23, v26
	v_pk_fma_f32 v[6:7], v[188:189], v[6:7], v[8:9] neg_lo:[1,0,0] neg_hi:[1,0,0]
	v_pk_mul_f32 v[22:23], v[22:23], v[136:137] op_sel_hi:[1,0]
	s_waitcnt vmcnt(2)
	v_mov_b32_e32 v24, v82
	s_waitcnt vmcnt(0)
	v_mov_b32_e32 v25, v86
	v_pk_mul_f32 v[8:9], v[6:7], v[6:7]
	v_pk_fma_f32 v[22:23], v[188:189], v[22:23], v[24:25] neg_lo:[1,0,0] neg_hi:[1,0,0]
	v_add_f32_e32 v8, v8, v9
	v_pk_mul_f32 v[24:25], v[22:23], v[22:23]
	v_mul_f32_e32 v10, v18, v36
	v_add_f32_e32 v8, v8, v24
	v_add_f32_e32 v8, v8, v25
	ds_bpermute_b32 v9, v137, v8
	s_nop 0
	v_cvt_pk_bf16_f32 v10, v10, v10
	ds_write_b16 v115, v10 offset:2912
	v_mul_f32_e32 v10, 0x45800000, v37
	v_cndmask_b32_e32 v10, v37, v10, vcc
	s_waitcnt lgkmcnt(1)
	v_add_f32_e32 v8, v8, v9
	ds_bpermute_b32 v9, v135, v8
	v_mul_f32_e32 v4, v4, v10
	v_mul_f32_e32 v4, v51, v4
	s_nop 0
	v_cvt_pk_bf16_f32 v4, v4, v4
	ds_write_b16 v115, v4 offset:2992
	s_waitcnt lgkmcnt(1)
	v_add_f32_e32 v8, v8, v9
	ds_bpermute_b32 v9, v133, v8
	v_mul_f32_e32 v4, v5, v10
	v_mul_f32_e32 v4, v50, v4
	s_nop 0
	v_cvt_pk_bf16_f32 v4, v4, v4
	ds_write_b16 v115, v4 offset:3056
	s_waitcnt lgkmcnt(1)
	v_add_f32_e32 v5, v8, v9
	ds_bpermute_b32 v8, v35, v5
	v_mul_f32_e32 v4, v20, v10
	v_mul_f32_e32 v4, v19, v4
	s_nop 0
	v_cvt_pk_bf16_f32 v4, v4, v4
	ds_write_b16 v115, v4 offset:3120
	s_waitcnt lgkmcnt(1)
	v_add_f32_e32 v5, v5, v8
	ds_bpermute_b32 v8, v3, v5
	v_mul_f32_e32 v4, v21, v10
	v_mul_f32_e32 v4, v18, v4
	s_nop 0
	v_cvt_pk_bf16_f32 v24, v4, v4
	v_mov_b32_e32 v58, v11
	s_waitcnt lgkmcnt(0)
	v_add_f32_e32 v4, v5, v8
	v_fmamk_f32 v25, v4, 0x3c000000, v187
	v_pk_mul_f32 v[4:5], v[58:59], v[134:135] op_sel_hi:[1,0]
	v_mov_b32_e32 v94, v91
	v_mov_b32_e32 v26, v43
	v_pk_fma_f32 v[4:5], v[188:189], v[4:5], v[94:95] neg_lo:[1,0,0] neg_hi:[1,0,0]
	v_pk_mul_f32 v[10:11], v[26:27], v[134:135] op_sel_hi:[1,0]
	v_mov_b32_e32 v86, v83
	v_pk_mul_f32 v[8:9], v[4:5], v[4:5]
	v_pk_fma_f32 v[10:11], v[188:189], v[10:11], v[86:87] neg_lo:[1,0,0] neg_hi:[1,0,0]
	v_add_f32_e32 v8, v8, v9
	v_pk_mul_f32 v[20:21], v[10:11], v[10:11]
	v_cmp_gt_f32_e32 vcc, s71, v25
	v_add_f32_e32 v8, v8, v20
	v_add_f32_e32 v8, v8, v21
	ds_bpermute_b32 v9, v137, v8
	v_mul_f32_e32 v20, 0x4b800000, v25
	v_cndmask_b32_e32 v20, v25, v20, vcc
	v_rsq_f32_e32 v20, v20
	ds_write_b16 v115, v24 offset:3184
	s_waitcnt lgkmcnt(1)
	v_add_f32_e32 v8, v8, v9
	ds_bpermute_b32 v9, v135, v8
	v_mul_f32_e32 v21, 0x45800000, v20
	v_cndmask_b32_e32 v20, v20, v21, vcc
	v_mul_f32_e32 v6, v6, v20
	v_mul_f32_e32 v6, v51, v6
	s_waitcnt lgkmcnt(0)
	v_add_f32_e32 v8, v8, v9
	ds_bpermute_b32 v9, v133, v8
	s_nop 0
	v_cvt_pk_bf16_f32 v6, v6, v6
	ds_write_b16 v115, v6 offset:4352
	v_mul_f32_e32 v6, v7, v20
	v_mul_f32_e32 v6, v50, v6
	s_waitcnt lgkmcnt(1)
	v_add_f32_e32 v7, v8, v9
	ds_bpermute_b32 v8, v35, v7
	s_nop 0
	v_cvt_pk_bf16_f32 v6, v6, v6
	ds_write_b16 v115, v6 offset:4416
	v_mul_f32_e32 v6, v22, v20
	v_mul_f32_e32 v6, v19, v6
	s_waitcnt lgkmcnt(1)
	v_add_f32_e32 v7, v7, v8
	ds_bpermute_b32 v8, v3, v7
	s_nop 0
	v_cvt_pk_bf16_f32 v6, v6, v6
	ds_write_b16 v115, v6 offset:4480
	v_mul_f32_e32 v24, v23, v20
	v_mov_b32_e32 v9, v96
	s_waitcnt lgkmcnt(1)
	v_add_f32_e32 v6, v7, v8
	v_fmamk_f32 v6, v6, 0x3c000000, v187
	v_mul_f32_e32 v7, 0x4b800000, v6
	v_cmp_gt_f32_e32 vcc, s71, v6
	v_mov_b32_e32 v8, v92
	v_mov_b32_e32 v20, v44
	v_cndmask_b32_e32 v6, v6, v7, vcc
	v_rsq_f32_e32 v25, v6
	v_mov_b32_e32 v6, v12
	v_mov_b32_e32 v7, v60
	v_pk_mul_f32 v[6:7], v[6:7], v[132:133] op_sel_hi:[1,0]
	v_mov_b32_e32 v21, v28
	v_pk_fma_f32 v[6:7], v[188:189], v[6:7], v[8:9] neg_lo:[1,0,0] neg_hi:[1,0,0]
	v_pk_mul_f32 v[20:21], v[20:21], v[132:133] op_sel_hi:[1,0]
	v_mov_b32_e32 v22, v84
	v_mov_b32_e32 v23, v88
	v_pk_mul_f32 v[8:9], v[6:7], v[6:7]
	v_pk_fma_f32 v[20:21], v[188:189], v[20:21], v[22:23] neg_lo:[1,0,0] neg_hi:[1,0,0]
	v_add_f32_e32 v8, v8, v9
	v_pk_mul_f32 v[22:23], v[20:21], v[20:21]
	v_mul_f32_e32 v12, v18, v24
	v_add_f32_e32 v8, v8, v22
	v_add_f32_e32 v8, v8, v23
	ds_bpermute_b32 v9, v137, v8
	s_nop 0
	v_cvt_pk_bf16_f32 v12, v12, v12
	ds_write_b16 v115, v12 offset:4544
	v_mul_f32_e32 v12, 0x45800000, v25
	v_cndmask_b32_e32 v12, v25, v12, vcc
	s_waitcnt lgkmcnt(1)
	v_add_f32_e32 v8, v8, v9
	ds_bpermute_b32 v9, v135, v8
	v_mul_f32_e32 v4, v4, v12
	v_mul_f32_e32 v4, v51, v4
	s_nop 0
	v_cvt_pk_bf16_f32 v4, v4, v4
	ds_write_b16 v115, v4 offset:4624
	s_waitcnt lgkmcnt(1)
	v_add_f32_e32 v8, v8, v9
	ds_bpermute_b32 v9, v133, v8
	v_mul_f32_e32 v4, v5, v12
	v_mul_f32_e32 v4, v50, v4
	s_nop 0
	v_cvt_pk_bf16_f32 v4, v4, v4
	ds_write_b16 v115, v4 offset:4688
	s_waitcnt lgkmcnt(1)
	v_add_f32_e32 v5, v8, v9
	ds_bpermute_b32 v8, v35, v5
	v_mul_f32_e32 v4, v10, v12
	v_mul_f32_e32 v4, v19, v4
	s_nop 0
	v_cvt_pk_bf16_f32 v4, v4, v4
	ds_write_b16 v115, v4 offset:4752
	s_waitcnt lgkmcnt(1)
	v_add_f32_e32 v5, v5, v8
	ds_bpermute_b32 v8, v3, v5
	v_mul_f32_e32 v4, v11, v12
	v_mul_f32_e32 v4, v18, v4
	s_nop 0
	v_cvt_pk_bf16_f32 v22, v4, v4
	v_mov_b32_e32 v60, v13
	s_waitcnt lgkmcnt(0)
; __device__ __forceinline__ u16 f2bf(float f) { return (u16)(cvtpk(f, f) & 0xffffu); }
; __device__ __forceinline__ void phase3(const Params& p, char* shm) {
;     ...
;         for (int q = 0; q < 4; ++q) { const f32x4 v1 = o1p[d0 * 4 + q];
; #pragma unroll
;           for (int e = 0; e < 4; ++e) o[d0][q * 4 + e] = v1[e] - lam * o[d0][q * 4 + e]; } }
;     float sw[4];
; #pragma unroll
;     for (int d0 = 0; d0 < 4; ++d0) sw[d0] = p.subln[d0 * 32 + r32] * 0.8f;
;     char* const otb = shm + ((wid * 32 + 4 * hi) * OT_LD + r32) * 2;
; #pragma unroll
;     for (int r = 0; r < 16; ++r) {
;       float ss = 0.f;
; #pragma unroll
;       for (int d0 = 0; d0 < 4; ++d0) ss += o[d0][r] * o[d0][r];
;       ss += __shfl_xor(ss, 1); ss += __shfl_xor(ss, 2); ss += __shfl_xor(ss, 4); ss += __shfl_xor(ss, 8); ss += __shfl_xor(ss, 16);
;       const float rstd = rsqrtf(ss * (1.f / 128.f) + 1e-6f);
; #pragma unroll
;       for (int d0 = 0; d0 < 4; ++d0) *(u16*)(otb + (((r & 3) + 8 * (r >> 2)) * OT_LD + d0 * 32) * 2) = f2bf(o[d0][r] * rstd * sw[d0]);
;     }
	v_add_f32_e32 v4, v5, v8
	v_fmamk_f32 v23, v4, 0x3c000000, v187
	v_pk_mul_f32 v[4:5], v[60:61], v[130:131] op_sel_hi:[1,0]
	v_mov_b32_e32 v96, v93
	v_mov_b32_e32 v28, v45
	v_pk_fma_f32 v[4:5], v[188:189], v[4:5], v[96:97] neg_lo:[1,0,0] neg_hi:[1,0,0]
	v_pk_mul_f32 v[10:11], v[28:29], v[130:131] op_sel_hi:[1,0]
	v_mov_b32_e32 v88, v85
	v_pk_mul_f32 v[8:9], v[4:5], v[4:5]
	v_pk_fma_f32 v[10:11], v[188:189], v[10:11], v[88:89] neg_lo:[1,0,0] neg_hi:[1,0,0]
	v_add_f32_e32 v8, v8, v9
	v_pk_mul_f32 v[12:13], v[10:11], v[10:11]
	v_cmp_gt_f32_e32 vcc, s71, v23
	v_add_f32_e32 v8, v8, v12
	v_add_f32_e32 v8, v8, v13
	ds_bpermute_b32 v9, v137, v8
	v_mul_f32_e32 v12, 0x4b800000, v23
	v_cndmask_b32_e32 v12, v23, v12, vcc
	v_rsq_f32_e32 v12, v12
	ds_write_b16 v115, v22 offset:4816
	s_waitcnt lgkmcnt(1)
	v_add_f32_e32 v8, v8, v9
	ds_bpermute_b32 v9, v135, v8
	v_mul_f32_e32 v13, 0x45800000, v12
	v_cndmask_b32_e32 v12, v12, v13, vcc
	v_mul_f32_e32 v6, v6, v12
	v_mul_f32_e32 v6, v51, v6
	s_waitcnt lgkmcnt(0)
	v_add_f32_e32 v8, v8, v9
	ds_bpermute_b32 v9, v133, v8
	s_nop 0
	v_cvt_pk_bf16_f32 v6, v6, v6
	ds_write_b16 v115, v6 offset:4896
	v_mul_f32_e32 v6, v7, v12
	v_mul_f32_e32 v6, v50, v6
	s_waitcnt lgkmcnt(1)
	v_add_f32_e32 v7, v8, v9
	ds_bpermute_b32 v8, v35, v7
	s_nop 0
	v_cvt_pk_bf16_f32 v6, v6, v6
	ds_write_b16 v115, v6 offset:4960
	v_mul_f32_e32 v6, v20, v12
	v_mul_f32_e32 v6, v19, v6
	s_waitcnt lgkmcnt(1)
	v_add_f32_e32 v7, v7, v8
	ds_bpermute_b32 v8, v3, v7
	s_nop 0
	v_cvt_pk_bf16_f32 v6, v6, v6
	ds_write_b16 v115, v6 offset:5024
	v_mul_f32_e32 v22, v21, v12
	v_mov_b32_e32 v9, v78
	s_waitcnt lgkmcnt(1)
	v_add_f32_e32 v6, v7, v8
	v_fmamk_f32 v6, v6, 0x3c000000, v187
	v_mul_f32_e32 v7, 0x4b800000, v6
	v_cmp_gt_f32_e32 vcc, s71, v6
	v_mov_b32_e32 v8, v74
	v_mov_b32_e32 v12, v46
	v_cndmask_b32_e32 v6, v6, v7, vcc
	v_rsq_f32_e32 v23, v6
	v_mov_b32_e32 v6, v14
	v_mov_b32_e32 v7, v62
	v_pk_mul_f32 v[6:7], v[6:7], v[118:119] op_sel_hi:[1,0]
	v_mov_b32_e32 v13, v30
	v_pk_fma_f32 v[6:7], v[188:189], v[6:7], v[8:9] neg_lo:[1,0,0] neg_hi:[1,0,0]
	v_pk_mul_f32 v[12:13], v[12:13], v[118:119] op_sel_hi:[1,0]
	v_mov_b32_e32 v20, v66
	v_mov_b32_e32 v21, v70
	v_pk_mul_f32 v[8:9], v[6:7], v[6:7]
	v_pk_fma_f32 v[12:13], v[188:189], v[12:13], v[20:21] neg_lo:[1,0,0] neg_hi:[1,0,0]
	v_add_f32_e32 v8, v8, v9
	v_pk_mul_f32 v[20:21], v[12:13], v[12:13]
	v_mul_f32_e32 v14, v18, v22
	v_add_f32_e32 v8, v8, v20
	v_add_f32_e32 v8, v8, v21
	ds_bpermute_b32 v9, v137, v8
	s_nop 0
	v_cvt_pk_bf16_f32 v14, v14, v14
	ds_write_b16 v115, v14 offset:5088
	v_mul_f32_e32 v14, 0x45800000, v23
	v_cndmask_b32_e32 v14, v23, v14, vcc
	s_waitcnt lgkmcnt(1)
	v_add_f32_e32 v8, v8, v9
	ds_bpermute_b32 v9, v135, v8
	v_mul_f32_e32 v4, v4, v14
	v_mul_f32_e32 v4, v51, v4
	s_nop 0
	v_cvt_pk_bf16_f32 v4, v4, v4
	ds_write_b16 v115, v4 offset:5168
	s_waitcnt lgkmcnt(1)
	v_add_f32_e32 v8, v8, v9
	ds_bpermute_b32 v9, v133, v8
	v_mul_f32_e32 v4, v5, v14
	v_mul_f32_e32 v4, v50, v4
	s_nop 0
	v_cvt_pk_bf16_f32 v4, v4, v4
	ds_write_b16 v115, v4 offset:5232
	s_waitcnt lgkmcnt(1)
	v_add_f32_e32 v5, v8, v9
	ds_bpermute_b32 v8, v35, v5
	v_mul_f32_e32 v4, v10, v14
	v_mul_f32_e32 v4, v19, v4
	s_nop 0
	v_cvt_pk_bf16_f32 v4, v4, v4
	ds_write_b16 v115, v4 offset:5296
	s_waitcnt lgkmcnt(1)
	v_add_f32_e32 v5, v5, v8
	ds_bpermute_b32 v8, v3, v5
	v_mul_f32_e32 v4, v11, v14
	v_mul_f32_e32 v4, v18, v4
	s_nop 0
	v_cvt_pk_bf16_f32 v20, v4, v4
	v_mov_b32_e32 v62, v15
	s_waitcnt lgkmcnt(0)
	v_add_f32_e32 v4, v5, v8
	v_fmamk_f32 v21, v4, 0x3c000000, v187
	v_pk_mul_f32 v[4:5], v[62:63], v[114:115] op_sel_hi:[1,0]
	v_mov_b32_e32 v78, v75
	v_mov_b32_e32 v30, v47
	v_pk_fma_f32 v[4:5], v[188:189], v[4:5], v[78:79] neg_lo:[1,0,0] neg_hi:[1,0,0]
	v_pk_mul_f32 v[10:11], v[30:31], v[114:115] op_sel_hi:[1,0]
	v_mov_b32_e32 v70, v67
	v_pk_mul_f32 v[8:9], v[4:5], v[4:5]
	v_pk_fma_f32 v[10:11], v[188:189], v[10:11], v[70:71] neg_lo:[1,0,0] neg_hi:[1,0,0]
	v_add_f32_e32 v8, v8, v9
	v_pk_mul_f32 v[14:15], v[10:11], v[10:11]
	v_cmp_gt_f32_e32 vcc, s71, v21
	v_add_f32_e32 v8, v8, v14
	v_add_f32_e32 v8, v8, v15
	ds_bpermute_b32 v9, v137, v8
	v_mul_f32_e32 v14, 0x4b800000, v21
	v_cndmask_b32_e32 v14, v21, v14, vcc
	v_rsq_f32_e32 v14, v14
	ds_write_b16 v115, v20 offset:5360
	s_waitcnt lgkmcnt(1)
	v_add_f32_e32 v8, v8, v9
	ds_bpermute_b32 v9, v135, v8
	v_mul_f32_e32 v15, 0x45800000, v14
	v_cndmask_b32_e32 v14, v14, v15, vcc
	v_mul_f32_e32 v6, v6, v14
	v_mul_f32_e32 v6, v51, v6
	s_waitcnt lgkmcnt(0)
	v_add_f32_e32 v8, v8, v9
	ds_bpermute_b32 v9, v133, v8
	s_nop 0
	v_cvt_pk_bf16_f32 v6, v6, v6
	ds_write_b16 v115, v6 offset:6528
	v_mul_f32_e32 v6, v7, v14
	v_mul_f32_e32 v6, v50, v6
	s_waitcnt lgkmcnt(1)
	v_add_f32_e32 v7, v8, v9
	ds_bpermute_b32 v8, v35, v7
	s_nop 0
	v_cvt_pk_bf16_f32 v6, v6, v6
	ds_write_b16 v115, v6 offset:6592
	v_mul_f32_e32 v6, v12, v14
	v_mul_f32_e32 v6, v19, v6
	s_waitcnt lgkmcnt(1)
	v_add_f32_e32 v7, v7, v8
	ds_bpermute_b32 v8, v3, v7
	s_nop 0
	v_cvt_pk_bf16_f32 v6, v6, v6
	ds_write_b16 v115, v6 offset:6656
	v_mul_f32_e32 v20, v13, v14
	v_mov_b32_e32 v9, v80
	s_waitcnt lgkmcnt(1)
	v_add_f32_e32 v6, v7, v8
	v_fmamk_f32 v6, v6, 0x3c000000, v187
	v_mul_f32_e32 v7, 0x4b800000, v6
	v_cmp_gt_f32_e32 vcc, s71, v6
	v_mov_b32_e32 v8, v76
	v_mov_b32_e32 v12, v48
	v_cndmask_b32_e32 v6, v6, v7, vcc
	v_rsq_f32_e32 v21, v6
	v_mov_b32_e32 v6, v16
	v_mov_b32_e32 v7, v64
	v_pk_mul_f32 v[6:7], v[6:7], v[34:35] op_sel_hi:[1,0]
	v_mov_b32_e32 v13, v32
	v_pk_fma_f32 v[6:7], v[188:189], v[6:7], v[8:9] neg_lo:[1,0,0] neg_hi:[1,0,0]
	v_pk_mul_f32 v[12:13], v[12:13], v[34:35] op_sel_hi:[1,0]
	v_mov_b32_e32 v14, v68
	v_mov_b32_e32 v15, v72
	v_pk_mul_f32 v[8:9], v[6:7], v[6:7]
	v_pk_fma_f32 v[12:13], v[188:189], v[12:13], v[14:15] neg_lo:[1,0,0] neg_hi:[1,0,0]
	v_add_f32_e32 v8, v8, v9
	v_pk_mul_f32 v[14:15], v[12:13], v[12:13]
	v_mov_b32_e32 v64, v17
	v_add_f32_e32 v8, v8, v14
	v_add_f32_e32 v8, v8, v15
	ds_bpermute_b32 v9, v137, v8
	v_mul_f32_e32 v14, v18, v20
	s_nop 0
	v_cvt_pk_bf16_f32 v14, v14, v14
	ds_write_b16 v115, v14 offset:6720
	v_mul_f32_e32 v14, 0x45800000, v21
	s_waitcnt lgkmcnt(1)
; __device__ __forceinline__ u16 f2bf(float f) { return (u16)(cvtpk(f, f) & 0xffffu); }
; __device__ __forceinline__ float bflo(unsigned v) { return __uint_as_float(v << 16); }
; __device__ __forceinline__ float bfhi(unsigned v) { return __uint_as_float(v & 0xffff0000u); }
; __device__ __forceinline__ void phase3(const Params& p, char* shm) {
;     ...
;     for (int r = 0; r < 16; ++r) {
;       float ss = 0.f;
; #pragma unroll
;       for (int d0 = 0; d0 < 4; ++d0) ss += o[d0][r] * o[d0][r];
;       ss += __shfl_xor(ss, 1); ss += __shfl_xor(ss, 2); ss += __shfl_xor(ss, 4); ss += __shfl_xor(ss, 8); ss += __shfl_xor(ss, 16);
;       const float rstd = rsqrtf(ss * (1.f / 128.f) + 1e-6f);
; #pragma unroll
;       for (int d0 = 0; d0 < 4; ++d0) *(u16*)(otb + (((r & 3) + 8 * (r >> 2)) * OT_LD + d0 * 32) * 2) = f2bf(o[d0][r] * rstd * sw[d0]);
;     }
;     __syncthreads();
;     { const u16* zsrc = Zb + t0 * AW + h * 128; u16* bdst = Bin + t0 * AW + h * 128;
; #pragma unroll 2
;       for (int id = tid; id < 256 * 16; id += NTHR) {
;         const int row = id >> 4, c = id & 15;
;         const u32x4 ov = *reinterpret_cast<const u32x4*>(shm + (row * OT_LD + c * 8) * 2);
;         const u32x4 zv = *reinterpret_cast<const u32x4*>(zsrc + (size_t)row * AW + c * 8);
;         u32x4 w;
; #pragma unroll
;         for (int q = 0; q < 4; ++q) w[q] = cvtpk(bflo(ov[q]) * bflo(zv[q]), bfhi(ov[q]) * bfhi(zv[q]));
;         *reinterpret_cast<u32x4*>(bdst + (size_t)row * AW + c * 8) = w;
;       }
	v_add_f32_e32 v8, v8, v9
	ds_bpermute_b32 v9, v135, v8
	v_cndmask_b32_e32 v14, v21, v14, vcc
	v_mul_f32_e32 v4, v4, v14
	v_mul_f32_e32 v4, v51, v4
	s_nop 0
	v_cvt_pk_bf16_f32 v4, v4, v4
	s_waitcnt lgkmcnt(0)
	v_add_f32_e32 v8, v8, v9
	ds_bpermute_b32 v9, v133, v8
	ds_write_b16 v115, v4 offset:6800
	v_mul_f32_e32 v4, v5, v14
	v_mul_f32_e32 v4, v50, v4
	s_nop 0
	v_cvt_pk_bf16_f32 v4, v4, v4
	s_waitcnt lgkmcnt(1)
	v_add_f32_e32 v5, v8, v9
	ds_bpermute_b32 v8, v35, v5
	ds_write_b16 v115, v4 offset:6864
	v_mul_f32_e32 v4, v10, v14
	v_mul_f32_e32 v4, v19, v4
	s_nop 0
	v_cvt_pk_bf16_f32 v4, v4, v4
	s_waitcnt lgkmcnt(1)
	v_add_f32_e32 v5, v5, v8
	ds_bpermute_b32 v8, v3, v5
	ds_write_b16 v115, v4 offset:6928
	v_mul_f32_e32 v4, v11, v14
	v_mul_f32_e32 v4, v18, v4
	s_nop 0
	v_cvt_pk_bf16_f32 v16, v4, v4
	s_waitcnt lgkmcnt(1)
	v_add_f32_e32 v4, v5, v8
	v_fmamk_f32 v20, v4, 0x3c000000, v187
	v_pk_mul_f32 v[4:5], v[64:65], v[2:3] op_sel_hi:[1,0]
	v_mov_b32_e32 v80, v77
	v_mov_b32_e32 v32, v49
	v_pk_fma_f32 v[4:5], v[188:189], v[4:5], v[80:81] neg_lo:[1,0,0] neg_hi:[1,0,0]
	v_pk_mul_f32 v[10:11], v[32:33], v[2:3] op_sel_hi:[1,0]
	v_mov_b32_e32 v72, v69
	v_pk_mul_f32 v[8:9], v[4:5], v[4:5]
	v_pk_fma_f32 v[10:11], v[188:189], v[10:11], v[72:73] neg_lo:[1,0,0] neg_hi:[1,0,0]
	v_add_f32_e32 v2, v8, v9
	v_pk_mul_f32 v[14:15], v[10:11], v[10:11]
	v_mul_f32_e32 v9, 0x4b800000, v20
	v_add_f32_e32 v2, v2, v14
	v_add_f32_e32 v2, v2, v15
	ds_bpermute_b32 v8, v137, v2
	v_cmp_gt_f32_e32 vcc, s71, v20
	ds_write_b16 v115, v16 offset:6992
	s_waitcnt lgkmcnt(1)
	v_add_f32_e32 v2, v2, v8
	ds_bpermute_b32 v8, v135, v2
	v_cndmask_b32_e32 v9, v20, v9, vcc
	v_rsq_f32_e32 v9, v9
	s_waitcnt lgkmcnt(0)
	v_add_f32_e32 v2, v2, v8
	ds_bpermute_b32 v8, v133, v2
	v_mul_f32_e32 v14, 0x45800000, v9
	v_cndmask_b32_e32 v9, v9, v14, vcc
	v_mul_f32_e32 v6, v6, v9
	v_mul_f32_e32 v6, v51, v6
	s_nop 0
	v_cvt_pk_bf16_f32 v6, v6, v6
	s_waitcnt lgkmcnt(0)
	v_add_f32_e32 v2, v2, v8
	ds_write_b16 v115, v6 offset:7072
	v_mul_f32_e32 v6, v7, v9
	ds_bpermute_b32 v7, v35, v2
	v_mul_f32_e32 v6, v50, v6
	s_nop 0
	v_cvt_pk_bf16_f32 v6, v6, v6
	ds_write_b16 v115, v6 offset:7136
	v_mul_f32_e32 v6, v12, v9
	s_waitcnt lgkmcnt(1)
	v_add_f32_e32 v2, v2, v7
	ds_bpermute_b32 v3, v3, v2
	v_mul_f32_e32 v6, v19, v6
	s_nop 0
	v_cvt_pk_bf16_f32 v6, v6, v6
	ds_write_b16 v115, v6 offset:7200
	v_mul_f32_e32 v6, v13, v9
	s_waitcnt lgkmcnt(1)
	v_add_f32_e32 v2, v2, v3
	v_fmamk_f32 v2, v2, 0x3c000000, v187
	v_mul_f32_e32 v3, 0x4b800000, v2
	v_cmp_gt_f32_e32 vcc, s71, v2
	s_nop 1
	v_cndmask_b32_e32 v2, v2, v3, vcc
	v_rsq_f32_e32 v2, v2
	v_mul_f32_e32 v3, v18, v6
	s_nop 0
	v_cvt_pk_bf16_f32 v3, v3, v3
	ds_write_b16 v115, v3 offset:7264
	v_mul_f32_e32 v3, 0x45800000, v2
	v_cndmask_b32_e32 v2, v2, v3, vcc
	v_mul_f32_e32 v3, v4, v2
	v_mul_f32_e32 v3, v51, v3
	s_nop 0
	v_cvt_pk_bf16_f32 v3, v3, v3
	ds_write_b16 v115, v3 offset:7344
	v_mul_f32_e32 v3, v5, v2
	v_mul_f32_e32 v3, v50, v3
	s_nop 0
	v_cvt_pk_bf16_f32 v3, v3, v3
	ds_write_b16 v115, v3 offset:7408
	v_mul_f32_e32 v3, v10, v2
	v_mul_f32_e32 v2, v11, v2
	v_mul_f32_e32 v3, v19, v3
	v_mul_f32_e32 v2, v18, v2
	v_cmp_gt_i32_e32 vcc, s72, v131
	s_nop 0
	v_cvt_pk_bf16_f32 v3, v3, v3
	ds_write_b16 v115, v3 offset:7472
	s_nop 0
	v_cvt_pk_bf16_f32 v2, v2, v2
	ds_write_b16 v115, v2 offset:7536
	s_waitcnt lgkmcnt(0)
	s_barrier
	s_and_saveexec_b64 s[0:1], vcc
	s_cbranch_execz .LBB0_322
	s_add_u32 s4, s79, s18
	s_addc_u32 s5, s80, s19
	s_add_u32 s4, s4, s86
	s_addc_u32 s5, s5, 0
	s_add_u32 s6, s81, s18
	s_addc_u32 s7, s82, s19
	s_add_u32 s6, s6, s86
	s_addc_u32 s7, s7, 0
	v_lshlrev_b32_e32 v2, 3, v131
	v_lshrrev_b32_e32 v52, 4, v131
	v_and_b32_e32 v53, 15, v131
	v_lshlrev_b32_e32 v54, 11, v52
	v_lshl_add_u32 v54, v53, 4, v54
	v_mul_u32_u24_e32 v52, 0x110, v52
	v_lshl_add_u32 v52, v53, 4, v52
	v_add_u32_e32 v55, 0x10000, v54
	v_add_u32_e32 v56, 0x20000, v54
	v_add_u32_e32 v57, 0x30000, v54
	v_add_u32_e32 v58, 0x40000, v54
	v_add_u32_e32 v59, 0x50000, v54
	v_add_u32_e32 v60, 0x60000, v54
	v_add_u32_e32 v61, 0x70000, v54
	global_load_dwordx4 v[4:7], v54, s[4:5]
	global_load_dwordx4 v[8:11], v55, s[4:5]
	global_load_dwordx4 v[12:15], v56, s[4:5]
	global_load_dwordx4 v[16:19], v57, s[4:5]
	global_load_dwordx4 v[20:23], v58, s[4:5]
	global_load_dwordx4 v[24:27], v59, s[4:5]
	global_load_dwordx4 v[28:31], v60, s[4:5]
	global_load_dwordx4 v[32:35], v61, s[4:5]
	ds_read_b128 v[36:39], v52
	ds_read_b128 v[40:43], v52 offset:8704
	ds_read_b128 v[44:47], v52 offset:17408
	ds_read_b128 v[48:51], v52 offset:26112
	s_waitcnt vmcnt(7) lgkmcnt(3)
	v_lshlrev_b32_e32 v62, 16, v36
	v_lshlrev_b32_e32 v63, 16, v4
	v_and_b32_e32 v36, 0xffff0000, v36
	v_and_b32_e32 v4, 0xffff0000, v4
	v_mul_f32_e32 v62, v63, v62
	v_mul_f32_e32 v4, v4, v36
	v_cvt_pk_bf16_f32 v4, v62, v4
	v_lshlrev_b32_e32 v62, 16, v37
	v_lshlrev_b32_e32 v63, 16, v5
	v_and_b32_e32 v37, 0xffff0000, v37
	v_and_b32_e32 v5, 0xffff0000, v5
	v_mul_f32_e32 v62, v63, v62
	v_mul_f32_e32 v5, v5, v37
	v_cvt_pk_bf16_f32 v5, v62, v5
	v_lshlrev_b32_e32 v62, 16, v38
	v_lshlrev_b32_e32 v63, 16, v6
	v_and_b32_e32 v38, 0xffff0000, v38
	v_and_b32_e32 v6, 0xffff0000, v6
	v_mul_f32_e32 v62, v63, v62
	v_mul_f32_e32 v6, v6, v38
	v_cvt_pk_bf16_f32 v6, v62, v6
	v_lshlrev_b32_e32 v62, 16, v39
	v_lshlrev_b32_e32 v63, 16, v7
	v_and_b32_e32 v39, 0xffff0000, v39
	v_and_b32_e32 v7, 0xffff0000, v7
	v_mul_f32_e32 v62, v63, v62
	v_mul_f32_e32 v7, v7, v39
	v_cvt_pk_bf16_f32 v7, v62, v7
	global_store_dwordx4 v54, v[4:7], s[6:7]
	s_waitcnt vmcnt(7) lgkmcnt(2)
; __device__ __forceinline__ float bflo(unsigned v) { return __uint_as_float(v << 16); }
; __device__ __forceinline__ float bfhi(unsigned v) { return __uint_as_float(v & 0xffff0000u); }
; __device__ __forceinline__ void phase3(const Params& p, char* shm) {
;     ...
;       for (int id = tid; id < 256 * 16; id += NTHR) {
;         const int row = id >> 4, c = id & 15;
;         const u32x4 ov = *reinterpret_cast<const u32x4*>(shm + (row * OT_LD + c * 8) * 2);
;         const u32x4 zv = *reinterpret_cast<const u32x4*>(zsrc + (size_t)row * AW + c * 8);
;         u32x4 w;
; #pragma unroll
;         for (int q = 0; q < 4; ++q) w[q] = cvtpk(bflo(ov[q]) * bflo(zv[q]), bfhi(ov[q]) * bfhi(zv[q]));
;         *reinterpret_cast<u32x4*>(bdst + (size_t)row * AW + c * 8) = w;
;       }
	v_lshlrev_b32_e32 v62, 16, v40
	v_lshlrev_b32_e32 v63, 16, v8
	v_and_b32_e32 v40, 0xffff0000, v40
	v_and_b32_e32 v8, 0xffff0000, v8
	v_mul_f32_e32 v62, v63, v62
	v_mul_f32_e32 v8, v8, v40
	v_cvt_pk_bf16_f32 v8, v62, v8
	v_lshlrev_b32_e32 v62, 16, v41
	v_lshlrev_b32_e32 v63, 16, v9
	v_and_b32_e32 v41, 0xffff0000, v41
	v_and_b32_e32 v9, 0xffff0000, v9
	v_mul_f32_e32 v62, v63, v62
	v_mul_f32_e32 v9, v9, v41
	v_cvt_pk_bf16_f32 v9, v62, v9
	v_lshlrev_b32_e32 v62, 16, v42
	v_lshlrev_b32_e32 v63, 16, v10
	v_and_b32_e32 v42, 0xffff0000, v42
	v_and_b32_e32 v10, 0xffff0000, v10
	v_mul_f32_e32 v62, v63, v62
	v_mul_f32_e32 v10, v10, v42
	v_cvt_pk_bf16_f32 v10, v62, v10
	v_lshlrev_b32_e32 v62, 16, v43
	v_lshlrev_b32_e32 v63, 16, v11
	v_and_b32_e32 v43, 0xffff0000, v43
	v_and_b32_e32 v11, 0xffff0000, v11
	v_mul_f32_e32 v62, v63, v62
	v_mul_f32_e32 v11, v11, v43
	v_cvt_pk_bf16_f32 v11, v62, v11
	global_store_dwordx4 v55, v[8:11], s[6:7]
	s_waitcnt vmcnt(7) lgkmcnt(1)
	v_lshlrev_b32_e32 v62, 16, v44
	v_lshlrev_b32_e32 v63, 16, v12
	v_and_b32_e32 v44, 0xffff0000, v44
	v_and_b32_e32 v12, 0xffff0000, v12
	v_mul_f32_e32 v62, v63, v62
	v_mul_f32_e32 v12, v12, v44
	v_cvt_pk_bf16_f32 v12, v62, v12
	v_lshlrev_b32_e32 v62, 16, v45
	v_lshlrev_b32_e32 v63, 16, v13
	v_and_b32_e32 v45, 0xffff0000, v45
	v_and_b32_e32 v13, 0xffff0000, v13
	v_mul_f32_e32 v62, v63, v62
	v_mul_f32_e32 v13, v13, v45
	v_cvt_pk_bf16_f32 v13, v62, v13
	v_lshlrev_b32_e32 v62, 16, v46
	v_lshlrev_b32_e32 v63, 16, v14
	v_and_b32_e32 v46, 0xffff0000, v46
	v_and_b32_e32 v14, 0xffff0000, v14
	v_mul_f32_e32 v62, v63, v62
	v_mul_f32_e32 v14, v14, v46
	v_cvt_pk_bf16_f32 v14, v62, v14
	v_lshlrev_b32_e32 v62, 16, v47
	v_lshlrev_b32_e32 v63, 16, v15
	v_and_b32_e32 v47, 0xffff0000, v47
	v_and_b32_e32 v15, 0xffff0000, v15
	v_mul_f32_e32 v62, v63, v62
	v_mul_f32_e32 v15, v15, v47
	v_cvt_pk_bf16_f32 v15, v62, v15
	global_store_dwordx4 v56, v[12:15], s[6:7]
	s_waitcnt vmcnt(7) lgkmcnt(0)
	v_lshlrev_b32_e32 v62, 16, v48
	v_lshlrev_b32_e32 v63, 16, v16
	v_and_b32_e32 v48, 0xffff0000, v48
	v_and_b32_e32 v16, 0xffff0000, v16
	v_mul_f32_e32 v62, v63, v62
	v_mul_f32_e32 v16, v16, v48
	v_cvt_pk_bf16_f32 v16, v62, v16
	v_lshlrev_b32_e32 v62, 16, v49
	v_lshlrev_b32_e32 v63, 16, v17
	v_and_b32_e32 v49, 0xffff0000, v49
	v_and_b32_e32 v17, 0xffff0000, v17
	v_mul_f32_e32 v62, v63, v62
	v_mul_f32_e32 v17, v17, v49
	v_cvt_pk_bf16_f32 v17, v62, v17
	v_lshlrev_b32_e32 v62, 16, v50
	v_lshlrev_b32_e32 v63, 16, v18
	v_and_b32_e32 v50, 0xffff0000, v50
	v_and_b32_e32 v18, 0xffff0000, v18
	v_mul_f32_e32 v62, v63, v62
	v_mul_f32_e32 v18, v18, v50
	v_cvt_pk_bf16_f32 v18, v62, v18
	v_lshlrev_b32_e32 v62, 16, v51
	v_lshlrev_b32_e32 v63, 16, v19
	v_and_b32_e32 v51, 0xffff0000, v51
	v_and_b32_e32 v19, 0xffff0000, v19
	v_mul_f32_e32 v62, v63, v62
	v_mul_f32_e32 v19, v19, v51
	v_cvt_pk_bf16_f32 v19, v62, v19
	global_store_dwordx4 v57, v[16:19], s[6:7]
	ds_read_b128 v[36:39], v52 offset:34816
	ds_read_b128 v[40:43], v52 offset:43520
	ds_read_b128 v[44:47], v52 offset:52224
	ds_read_b128 v[48:51], v52 offset:60928
	s_waitcnt vmcnt(7) lgkmcnt(3)
	v_lshlrev_b32_e32 v62, 16, v36
	v_lshlrev_b32_e32 v63, 16, v20
	v_and_b32_e32 v36, 0xffff0000, v36
	v_and_b32_e32 v20, 0xffff0000, v20
	v_mul_f32_e32 v62, v63, v62
	v_mul_f32_e32 v20, v20, v36
	v_cvt_pk_bf16_f32 v20, v62, v20
	v_lshlrev_b32_e32 v62, 16, v37
	v_lshlrev_b32_e32 v63, 16, v21
	v_and_b32_e32 v37, 0xffff0000, v37
	v_and_b32_e32 v21, 0xffff0000, v21
	v_mul_f32_e32 v62, v63, v62
	v_mul_f32_e32 v21, v21, v37
	v_cvt_pk_bf16_f32 v21, v62, v21
	v_lshlrev_b32_e32 v62, 16, v38
	v_lshlrev_b32_e32 v63, 16, v22
	v_and_b32_e32 v38, 0xffff0000, v38
	v_and_b32_e32 v22, 0xffff0000, v22
	v_mul_f32_e32 v62, v63, v62
	v_mul_f32_e32 v22, v22, v38
	v_cvt_pk_bf16_f32 v22, v62, v22
	v_lshlrev_b32_e32 v62, 16, v39
	v_lshlrev_b32_e32 v63, 16, v23
	v_and_b32_e32 v39, 0xffff0000, v39
	v_and_b32_e32 v23, 0xffff0000, v23
	v_mul_f32_e32 v62, v63, v62
	v_mul_f32_e32 v23, v23, v39
	v_cvt_pk_bf16_f32 v23, v62, v23
	global_store_dwordx4 v58, v[20:23], s[6:7]
	s_waitcnt vmcnt(7) lgkmcnt(2)
; __device__ __forceinline__ float bflo(unsigned v) { return __uint_as_float(v << 16); }
; __device__ __forceinline__ float bfhi(unsigned v) { return __uint_as_float(v & 0xffff0000u); }
; __device__ __forceinline__ void phase3(const Params& p, char* shm) {
;     ...
;       for (int id = tid; id < 256 * 16; id += NTHR) {
;         const int row = id >> 4, c = id & 15;
;         const u32x4 ov = *reinterpret_cast<const u32x4*>(shm + (row * OT_LD + c * 8) * 2);
;         const u32x4 zv = *reinterpret_cast<const u32x4*>(zsrc + (size_t)row * AW + c * 8);
;         u32x4 w;
; #pragma unroll
;         for (int q = 0; q < 4; ++q) w[q] = cvtpk(bflo(ov[q]) * bflo(zv[q]), bfhi(ov[q]) * bfhi(zv[q]));
;         *reinterpret_cast<u32x4*>(bdst + (size_t)row * AW + c * 8) = w;
;       }
	v_lshlrev_b32_e32 v62, 16, v40
	v_lshlrev_b32_e32 v63, 16, v24
	v_and_b32_e32 v40, 0xffff0000, v40
	v_and_b32_e32 v24, 0xffff0000, v24
	v_mul_f32_e32 v62, v63, v62
	v_mul_f32_e32 v24, v24, v40
	v_cvt_pk_bf16_f32 v24, v62, v24
	v_lshlrev_b32_e32 v62, 16, v41
	v_lshlrev_b32_e32 v63, 16, v25
	v_and_b32_e32 v41, 0xffff0000, v41
	v_and_b32_e32 v25, 0xffff0000, v25
	v_mul_f32_e32 v62, v63, v62
	v_mul_f32_e32 v25, v25, v41
	v_cvt_pk_bf16_f32 v25, v62, v25
	v_lshlrev_b32_e32 v62, 16, v42
	v_lshlrev_b32_e32 v63, 16, v26
	v_and_b32_e32 v42, 0xffff0000, v42
	v_and_b32_e32 v26, 0xffff0000, v26
	v_mul_f32_e32 v62, v63, v62
	v_mul_f32_e32 v26, v26, v42
	v_cvt_pk_bf16_f32 v26, v62, v26
	v_lshlrev_b32_e32 v62, 16, v43
	v_lshlrev_b32_e32 v63, 16, v27
	v_and_b32_e32 v43, 0xffff0000, v43
	v_and_b32_e32 v27, 0xffff0000, v27
	v_mul_f32_e32 v62, v63, v62
	v_mul_f32_e32 v27, v27, v43
	v_cvt_pk_bf16_f32 v27, v62, v27
	global_store_dwordx4 v59, v[24:27], s[6:7]
	s_waitcnt vmcnt(7) lgkmcnt(1)
	v_lshlrev_b32_e32 v62, 16, v44
	v_lshlrev_b32_e32 v63, 16, v28
	v_and_b32_e32 v44, 0xffff0000, v44
	v_and_b32_e32 v28, 0xffff0000, v28
	v_mul_f32_e32 v62, v63, v62
	v_mul_f32_e32 v28, v28, v44
	v_cvt_pk_bf16_f32 v28, v62, v28
	v_lshlrev_b32_e32 v62, 16, v45
	v_lshlrev_b32_e32 v63, 16, v29
	v_and_b32_e32 v45, 0xffff0000, v45
	v_and_b32_e32 v29, 0xffff0000, v29
	v_mul_f32_e32 v62, v63, v62
	v_mul_f32_e32 v29, v29, v45
	v_cvt_pk_bf16_f32 v29, v62, v29
	v_lshlrev_b32_e32 v62, 16, v46
	v_lshlrev_b32_e32 v63, 16, v30
	v_and_b32_e32 v46, 0xffff0000, v46
	v_and_b32_e32 v30, 0xffff0000, v30
	v_mul_f32_e32 v62, v63, v62
	v_mul_f32_e32 v30, v30, v46
	v_cvt_pk_bf16_f32 v30, v62, v30
	v_lshlrev_b32_e32 v62, 16, v47
	v_lshlrev_b32_e32 v63, 16, v31
	v_and_b32_e32 v47, 0xffff0000, v47
	v_and_b32_e32 v31, 0xffff0000, v31
	v_mul_f32_e32 v62, v63, v62
	v_mul_f32_e32 v31, v31, v47
	v_cvt_pk_bf16_f32 v31, v62, v31
	global_store_dwordx4 v60, v[28:31], s[6:7]
	s_waitcnt vmcnt(7) lgkmcnt(0)
	v_lshlrev_b32_e32 v62, 16, v48
	v_lshlrev_b32_e32 v63, 16, v32
	v_and_b32_e32 v48, 0xffff0000, v48
	v_and_b32_e32 v32, 0xffff0000, v32
	v_mul_f32_e32 v62, v63, v62
	v_mul_f32_e32 v32, v32, v48
	v_cvt_pk_bf16_f32 v32, v62, v32
	v_lshlrev_b32_e32 v62, 16, v49
	v_lshlrev_b32_e32 v63, 16, v33
	v_and_b32_e32 v49, 0xffff0000, v49
	v_and_b32_e32 v33, 0xffff0000, v33
	v_mul_f32_e32 v62, v63, v62
	v_mul_f32_e32 v33, v33, v49
	v_cvt_pk_bf16_f32 v33, v62, v33
	v_lshlrev_b32_e32 v62, 16, v50
	v_lshlrev_b32_e32 v63, 16, v34
	v_and_b32_e32 v50, 0xffff0000, v50
	v_and_b32_e32 v34, 0xffff0000, v34
	v_mul_f32_e32 v62, v63, v62
	v_mul_f32_e32 v34, v34, v50
	v_cvt_pk_bf16_f32 v34, v62, v34
	v_lshlrev_b32_e32 v62, 16, v51
	v_lshlrev_b32_e32 v63, 16, v35
	v_and_b32_e32 v51, 0xffff0000, v51
	v_and_b32_e32 v35, 0xffff0000, v35
	v_mul_f32_e32 v62, v63, v62
	v_mul_f32_e32 v35, v35, v51
	v_cvt_pk_bf16_f32 v35, v62, v35
	global_store_dwordx4 v61, v[32:35], s[6:7]
	v_add_u32_e32 v131, 0x1000, v131
	v_and_b32_e32 v190, 0x78, v2
	v_lshlrev_b32_e32 v190, 1, v190
	v_add_u32_e32 v2, 0x8000, v2
	s_mov_b64 s[18:19], exec
	s_nop 1
	s_branch .LBB0_322
